# RWKV scan LDS prefetch one step ahead instead of two (at most 15 LDS ops outstanding per wave)
# baseline (speedup 1.0000x reference)
.Lrw_scan_loop:
	s_and_b32 s2, s8, 1
	s_mul_i32 s3, s2, 0xe000
	s_lshl_b32 s2, s2, 12
	v_add_u32_e32 v195, s3, v103
	v_add_u32_e32 v33, s3, v38
	v_add_u32_e32 v196, s3, v75
	v_add_u32_e32 v36, s3, v37
	v_add_u32_e32 v102, s2, v76
	ds_read_b128 v[140:143], v195 offset:0
	ds_read_b128 v[152:155], v195 offset:8192
	ds_read_b128 v[164:167], v195 offset:24576
	ds_read_b128 v[176:179], v195 offset:16384
	ds_read_b128 v[84:87], v195 offset:32768
	ds_read_b64 v[4:5], v196 offset:0
	ds_read_b64 v[6:7], v36 offset:0
	ds_read_b128 v[144:147], v195 offset:256
	ds_read_b128 v[156:159], v195 offset:8448
	ds_read_b128 v[168:171], v195 offset:24832
	ds_read_b128 v[180:183], v195 offset:16640
	ds_read_b128 v[88:91], v195 offset:33024
	ds_read_b64 v[8:9], v196 offset:512
	ds_read_b64 v[10:11], v36 offset:512
	s_waitcnt lgkmcnt(7)
	v_pk_mul_f32 v[46:47], v[24:25], v[140:141] op_sel_hi:[0,1]
	v_pk_mul_f32 v[34:35], v[20:21], v[140:141] op_sel_hi:[0,1]
	v_pk_fma_f32 v[46:47], v[24:25], v[142:143], v[46:47] op_sel:[1,0,0] op_sel_hi:[1,1,1]
	v_pk_fma_f32 v[34:35], v[20:21], v[142:143], v[34:35] op_sel:[1,0,0] op_sel_hi:[1,1,1]
	v_pk_fma_f32 v[46:47], v[26:27], v[152:153], v[46:47] op_sel_hi:[0,1,1]
	v_pk_fma_f32 v[34:35], v[22:23], v[152:153], v[34:35] op_sel_hi:[0,1,1]
	v_pk_fma_f32 v[46:47], v[26:27], v[154:155], v[46:47] op_sel:[1,0,0] op_sel_hi:[1,1,1]
	v_pk_fma_f32 v[34:35], v[22:23], v[154:155], v[34:35] op_sel:[1,0,0] op_sel_hi:[1,1,1]
	v_pk_mul_f32 v[20:21], v[20:21], v[164:165]
	v_add_f32_dpp v28, v46, v34 row_half_mirror row_mask:0xf bank_mask:0xf
	v_add_f32_dpp v32, v47, v35 row_half_mirror row_mask:0xf bank_mask:0xf
	v_pk_mul_f32 v[22:23], v[22:23], v[166:167]
	v_add_f32_dpp v28, v28, v28 row_ror:8 row_mask:0xf bank_mask:0xf
	v_add_f32_dpp v32, v32, v32 row_ror:8 row_mask:0xf bank_mask:0xf
	v_pk_mul_f32 v[24:25], v[24:25], v[164:165]
	v_add_f32_dpp v28, v28, v28 quad_perm:[1,0,3,2] row_mask:0xf bank_mask:0xf
	v_add_f32_dpp v32, v32, v32 quad_perm:[1,0,3,2] row_mask:0xf bank_mask:0xf
	v_pk_mul_f32 v[26:27], v[26:27], v[166:167]
	v_add_f32_dpp v28, v28, v28 quad_perm:[2,3,0,1] row_mask:0xf bank_mask:0xf
	v_add_f32_dpp v32, v32, v32 quad_perm:[2,3,0,1] row_mask:0xf bank_mask:0xf
	v_pk_fma_f32 v[20:21], v[176:177], v[4:5], v[20:21] op_sel_hi:[1,0,1]
	v_mov_b32_dpp v30, v28 row_half_mirror row_mask:0xf bank_mask:0xf
	v_pk_fma_f32 v[22:23], v[178:179], v[4:5], v[22:23] op_sel_hi:[1,0,1]
	v_pk_fma_f32 v[24:25], v[176:177], v[6:7], v[24:25] op_sel_hi:[1,0,1]
	v_pk_fma_f32 v[26:27], v[178:179], v[6:7], v[26:27] op_sel_hi:[1,0,1]
	v_pk_fma_f32 v[20:21], v[84:85], v[28:29], v[20:21] op_sel_hi:[1,0,1] neg_lo:[0,1,0] neg_hi:[0,1,0]
	v_pk_fma_f32 v[22:23], v[86:87], v[28:29], v[22:23] op_sel_hi:[1,0,1] neg_lo:[0,1,0] neg_hi:[0,1,0]
	v_pk_fma_f32 v[24:25], v[84:85], v[30:31], v[24:25] op_sel_hi:[1,0,1] neg_lo:[0,1,0] neg_hi:[0,1,0]
	v_pk_fma_f32 v[26:27], v[86:87], v[30:31], v[26:27] op_sel_hi:[1,0,1] neg_lo:[0,1,0] neg_hi:[0,1,0]
	v_add_f32_e32 v39, v32, v5
	ds_write_b32 v102, v39 offset:0
	ds_read_b128 v[140:143], v195 offset:512
	ds_read_b128 v[152:155], v195 offset:8704
	ds_read_b128 v[164:167], v195 offset:25088
	ds_read_b128 v[176:179], v195 offset:16896
	ds_read_b128 v[84:87], v195 offset:33280
	ds_read_b64 v[4:5], v196 offset:1024
	ds_read_b64 v[6:7], v36 offset:1024
	s_waitcnt lgkmcnt(8)
	v_pk_mul_f32 v[46:47], v[24:25], v[144:145] op_sel_hi:[0,1]
	v_pk_mul_f32 v[34:35], v[20:21], v[144:145] op_sel_hi:[0,1]
	v_pk_fma_f32 v[46:47], v[24:25], v[146:147], v[46:47] op_sel:[1,0,0] op_sel_hi:[1,1,1]
	v_pk_fma_f32 v[34:35], v[20:21], v[146:147], v[34:35] op_sel:[1,0,0] op_sel_hi:[1,1,1]
	v_pk_fma_f32 v[46:47], v[26:27], v[156:157], v[46:47] op_sel_hi:[0,1,1]
	v_pk_fma_f32 v[34:35], v[22:23], v[156:157], v[34:35] op_sel_hi:[0,1,1]
	v_pk_fma_f32 v[46:47], v[26:27], v[158:159], v[46:47] op_sel:[1,0,0] op_sel_hi:[1,1,1]
	v_pk_fma_f32 v[34:35], v[22:23], v[158:159], v[34:35] op_sel:[1,0,0] op_sel_hi:[1,1,1]
	v_pk_mul_f32 v[20:21], v[20:21], v[168:169]
	v_add_f32_dpp v28, v46, v34 row_half_mirror row_mask:0xf bank_mask:0xf
	v_add_f32_dpp v32, v47, v35 row_half_mirror row_mask:0xf bank_mask:0xf
	v_pk_mul_f32 v[22:23], v[22:23], v[170:171]
	v_add_f32_dpp v28, v28, v28 row_ror:8 row_mask:0xf bank_mask:0xf
	v_add_f32_dpp v32, v32, v32 row_ror:8 row_mask:0xf bank_mask:0xf
	v_pk_mul_f32 v[24:25], v[24:25], v[168:169]
	v_add_f32_dpp v28, v28, v28 quad_perm:[1,0,3,2] row_mask:0xf bank_mask:0xf
	v_add_f32_dpp v32, v32, v32 quad_perm:[1,0,3,2] row_mask:0xf bank_mask:0xf
	v_pk_mul_f32 v[26:27], v[26:27], v[170:171]
	v_add_f32_dpp v28, v28, v28 quad_perm:[2,3,0,1] row_mask:0xf bank_mask:0xf
	v_add_f32_dpp v32, v32, v32 quad_perm:[2,3,0,1] row_mask:0xf bank_mask:0xf
	v_pk_fma_f32 v[20:21], v[180:181], v[8:9], v[20:21] op_sel_hi:[1,0,1]
	v_mov_b32_dpp v30, v28 row_half_mirror row_mask:0xf bank_mask:0xf
	v_pk_fma_f32 v[22:23], v[182:183], v[8:9], v[22:23] op_sel_hi:[1,0,1]
	v_pk_fma_f32 v[24:25], v[180:181], v[10:11], v[24:25] op_sel_hi:[1,0,1]
	v_pk_fma_f32 v[26:27], v[182:183], v[10:11], v[26:27] op_sel_hi:[1,0,1]
	v_pk_fma_f32 v[20:21], v[88:89], v[28:29], v[20:21] op_sel_hi:[1,0,1] neg_lo:[0,1,0] neg_hi:[0,1,0]
	v_pk_fma_f32 v[22:23], v[90:91], v[28:29], v[22:23] op_sel_hi:[1,0,1] neg_lo:[0,1,0] neg_hi:[0,1,0]
	v_pk_fma_f32 v[24:25], v[88:89], v[30:31], v[24:25] op_sel_hi:[1,0,1] neg_lo:[0,1,0] neg_hi:[0,1,0]
	v_pk_fma_f32 v[26:27], v[90:91], v[30:31], v[26:27] op_sel_hi:[1,0,1] neg_lo:[0,1,0] neg_hi:[0,1,0]
	v_add_f32_e32 v39, v32, v9
	ds_write_b32 v102, v39 offset:128
	ds_read_b128 v[144:147], v195 offset:768
	ds_read_b128 v[156:159], v195 offset:8960
	ds_read_b128 v[168:171], v195 offset:25344
	ds_read_b128 v[180:183], v195 offset:17152
	ds_read_b128 v[88:91], v195 offset:33536
	ds_read_b64 v[8:9], v196 offset:1536
	ds_read_b64 v[10:11], v36 offset:1536
	s_waitcnt lgkmcnt(8)
	v_pk_mul_f32 v[46:47], v[24:25], v[140:141] op_sel_hi:[0,1]
	v_pk_mul_f32 v[34:35], v[20:21], v[140:141] op_sel_hi:[0,1]
	v_pk_fma_f32 v[46:47], v[24:25], v[142:143], v[46:47] op_sel:[1,0,0] op_sel_hi:[1,1,1]
	v_pk_fma_f32 v[34:35], v[20:21], v[142:143], v[34:35] op_sel:[1,0,0] op_sel_hi:[1,1,1]
	v_pk_fma_f32 v[46:47], v[26:27], v[152:153], v[46:47] op_sel_hi:[0,1,1]
	v_pk_fma_f32 v[34:35], v[22:23], v[152:153], v[34:35] op_sel_hi:[0,1,1]
	v_pk_fma_f32 v[46:47], v[26:27], v[154:155], v[46:47] op_sel:[1,0,0] op_sel_hi:[1,1,1]
	v_pk_fma_f32 v[34:35], v[22:23], v[154:155], v[34:35] op_sel:[1,0,0] op_sel_hi:[1,1,1]
	v_pk_mul_f32 v[20:21], v[20:21], v[164:165]
	v_add_f32_dpp v28, v46, v34 row_half_mirror row_mask:0xf bank_mask:0xf
	v_add_f32_dpp v32, v47, v35 row_half_mirror row_mask:0xf bank_mask:0xf
	v_pk_mul_f32 v[22:23], v[22:23], v[166:167]
	v_add_f32_dpp v28, v28, v28 row_ror:8 row_mask:0xf bank_mask:0xf
	v_add_f32_dpp v32, v32, v32 row_ror:8 row_mask:0xf bank_mask:0xf
	v_pk_mul_f32 v[24:25], v[24:25], v[164:165]
	v_add_f32_dpp v28, v28, v28 quad_perm:[1,0,3,2] row_mask:0xf bank_mask:0xf
	v_add_f32_dpp v32, v32, v32 quad_perm:[1,0,3,2] row_mask:0xf bank_mask:0xf
	v_pk_mul_f32 v[26:27], v[26:27], v[166:167]
	v_add_f32_dpp v28, v28, v28 quad_perm:[2,3,0,1] row_mask:0xf bank_mask:0xf
	v_add_f32_dpp v32, v32, v32 quad_perm:[2,3,0,1] row_mask:0xf bank_mask:0xf
	v_pk_fma_f32 v[20:21], v[176:177], v[4:5], v[20:21] op_sel_hi:[1,0,1]
	v_mov_b32_dpp v30, v28 row_half_mirror row_mask:0xf bank_mask:0xf
	v_pk_fma_f32 v[22:23], v[178:179], v[4:5], v[22:23] op_sel_hi:[1,0,1]
	v_pk_fma_f32 v[24:25], v[176:177], v[6:7], v[24:25] op_sel_hi:[1,0,1]
	v_pk_fma_f32 v[26:27], v[178:179], v[6:7], v[26:27] op_sel_hi:[1,0,1]
	v_pk_fma_f32 v[20:21], v[84:85], v[28:29], v[20:21] op_sel_hi:[1,0,1] neg_lo:[0,1,0] neg_hi:[0,1,0]
	v_pk_fma_f32 v[22:23], v[86:87], v[28:29], v[22:23] op_sel_hi:[1,0,1] neg_lo:[0,1,0] neg_hi:[0,1,0]
	v_pk_fma_f32 v[24:25], v[84:85], v[30:31], v[24:25] op_sel_hi:[1,0,1] neg_lo:[0,1,0] neg_hi:[0,1,0]
	v_pk_fma_f32 v[26:27], v[86:87], v[30:31], v[26:27] op_sel_hi:[1,0,1] neg_lo:[0,1,0] neg_hi:[0,1,0]
	v_add_f32_e32 v39, v32, v5
	ds_write_b32 v102, v39 offset:256
	ds_read_b128 v[140:143], v195 offset:1024
	ds_read_b128 v[152:155], v195 offset:9216
	ds_read_b128 v[164:167], v195 offset:25600
	ds_read_b128 v[176:179], v195 offset:17408
	ds_read_b128 v[84:87], v195 offset:33792
	ds_read_b64 v[4:5], v196 offset:2048
	ds_read_b64 v[6:7], v36 offset:2048
	s_waitcnt lgkmcnt(8)
	v_pk_mul_f32 v[46:47], v[24:25], v[144:145] op_sel_hi:[0,1]
	v_pk_mul_f32 v[34:35], v[20:21], v[144:145] op_sel_hi:[0,1]
	v_pk_fma_f32 v[46:47], v[24:25], v[146:147], v[46:47] op_sel:[1,0,0] op_sel_hi:[1,1,1]
	v_pk_fma_f32 v[34:35], v[20:21], v[146:147], v[34:35] op_sel:[1,0,0] op_sel_hi:[1,1,1]
	v_pk_fma_f32 v[46:47], v[26:27], v[156:157], v[46:47] op_sel_hi:[0,1,1]
	v_pk_fma_f32 v[34:35], v[22:23], v[156:157], v[34:35] op_sel_hi:[0,1,1]
	v_pk_fma_f32 v[46:47], v[26:27], v[158:159], v[46:47] op_sel:[1,0,0] op_sel_hi:[1,1,1]
	v_pk_fma_f32 v[34:35], v[22:23], v[158:159], v[34:35] op_sel:[1,0,0] op_sel_hi:[1,1,1]
	v_pk_mul_f32 v[20:21], v[20:21], v[168:169]
	v_add_f32_dpp v28, v46, v34 row_half_mirror row_mask:0xf bank_mask:0xf
	v_add_f32_dpp v32, v47, v35 row_half_mirror row_mask:0xf bank_mask:0xf
	v_pk_mul_f32 v[22:23], v[22:23], v[170:171]
	v_add_f32_dpp v28, v28, v28 row_ror:8 row_mask:0xf bank_mask:0xf
	v_add_f32_dpp v32, v32, v32 row_ror:8 row_mask:0xf bank_mask:0xf
	v_pk_mul_f32 v[24:25], v[24:25], v[168:169]
	v_add_f32_dpp v28, v28, v28 quad_perm:[1,0,3,2] row_mask:0xf bank_mask:0xf
	v_add_f32_dpp v32, v32, v32 quad_perm:[1,0,3,2] row_mask:0xf bank_mask:0xf
	v_pk_mul_f32 v[26:27], v[26:27], v[170:171]
	v_add_f32_dpp v28, v28, v28 quad_perm:[2,3,0,1] row_mask:0xf bank_mask:0xf
	v_add_f32_dpp v32, v32, v32 quad_perm:[2,3,0,1] row_mask:0xf bank_mask:0xf
	v_pk_fma_f32 v[20:21], v[180:181], v[8:9], v[20:21] op_sel_hi:[1,0,1]
	v_mov_b32_dpp v30, v28 row_half_mirror row_mask:0xf bank_mask:0xf
	v_pk_fma_f32 v[22:23], v[182:183], v[8:9], v[22:23] op_sel_hi:[1,0,1]
	v_pk_fma_f32 v[24:25], v[180:181], v[10:11], v[24:25] op_sel_hi:[1,0,1]
	v_pk_fma_f32 v[26:27], v[182:183], v[10:11], v[26:27] op_sel_hi:[1,0,1]
	v_pk_fma_f32 v[20:21], v[88:89], v[28:29], v[20:21] op_sel_hi:[1,0,1] neg_lo:[0,1,0] neg_hi:[0,1,0]
	v_pk_fma_f32 v[22:23], v[90:91], v[28:29], v[22:23] op_sel_hi:[1,0,1] neg_lo:[0,1,0] neg_hi:[0,1,0]
	v_pk_fma_f32 v[24:25], v[88:89], v[30:31], v[24:25] op_sel_hi:[1,0,1] neg_lo:[0,1,0] neg_hi:[0,1,0]
	v_pk_fma_f32 v[26:27], v[90:91], v[30:31], v[26:27] op_sel_hi:[1,0,1] neg_lo:[0,1,0] neg_hi:[0,1,0]
	v_add_f32_e32 v39, v32, v9
	ds_write_b32 v102, v39 offset:384
	ds_read_b128 v[144:147], v195 offset:1280
	ds_read_b128 v[156:159], v195 offset:9472
	ds_read_b128 v[168:171], v195 offset:25856
	ds_read_b128 v[180:183], v195 offset:17664
	ds_read_b128 v[88:91], v195 offset:34048
	ds_read_b64 v[8:9], v196 offset:2560
	ds_read_b64 v[10:11], v36 offset:2560
	s_waitcnt lgkmcnt(8)
	v_pk_mul_f32 v[46:47], v[24:25], v[140:141] op_sel_hi:[0,1]
	v_pk_mul_f32 v[34:35], v[20:21], v[140:141] op_sel_hi:[0,1]
	v_pk_fma_f32 v[46:47], v[24:25], v[142:143], v[46:47] op_sel:[1,0,0] op_sel_hi:[1,1,1]
	v_pk_fma_f32 v[34:35], v[20:21], v[142:143], v[34:35] op_sel:[1,0,0] op_sel_hi:[1,1,1]
	v_pk_fma_f32 v[46:47], v[26:27], v[152:153], v[46:47] op_sel_hi:[0,1,1]
	v_pk_fma_f32 v[34:35], v[22:23], v[152:153], v[34:35] op_sel_hi:[0,1,1]
	v_pk_fma_f32 v[46:47], v[26:27], v[154:155], v[46:47] op_sel:[1,0,0] op_sel_hi:[1,1,1]
	v_pk_fma_f32 v[34:35], v[22:23], v[154:155], v[34:35] op_sel:[1,0,0] op_sel_hi:[1,1,1]
	v_pk_mul_f32 v[20:21], v[20:21], v[164:165]
	v_add_f32_dpp v28, v46, v34 row_half_mirror row_mask:0xf bank_mask:0xf
	v_add_f32_dpp v32, v47, v35 row_half_mirror row_mask:0xf bank_mask:0xf
	v_pk_mul_f32 v[22:23], v[22:23], v[166:167]
	v_add_f32_dpp v28, v28, v28 row_ror:8 row_mask:0xf bank_mask:0xf
	v_add_f32_dpp v32, v32, v32 row_ror:8 row_mask:0xf bank_mask:0xf
	v_pk_mul_f32 v[24:25], v[24:25], v[164:165]
	v_add_f32_dpp v28, v28, v28 quad_perm:[1,0,3,2] row_mask:0xf bank_mask:0xf
	v_add_f32_dpp v32, v32, v32 quad_perm:[1,0,3,2] row_mask:0xf bank_mask:0xf
	v_pk_mul_f32 v[26:27], v[26:27], v[166:167]
	v_add_f32_dpp v28, v28, v28 quad_perm:[2,3,0,1] row_mask:0xf bank_mask:0xf
	v_add_f32_dpp v32, v32, v32 quad_perm:[2,3,0,1] row_mask:0xf bank_mask:0xf
	v_pk_fma_f32 v[20:21], v[176:177], v[4:5], v[20:21] op_sel_hi:[1,0,1]
	v_mov_b32_dpp v30, v28 row_half_mirror row_mask:0xf bank_mask:0xf
	v_pk_fma_f32 v[22:23], v[178:179], v[4:5], v[22:23] op_sel_hi:[1,0,1]
	v_pk_fma_f32 v[24:25], v[176:177], v[6:7], v[24:25] op_sel_hi:[1,0,1]
	v_pk_fma_f32 v[26:27], v[178:179], v[6:7], v[26:27] op_sel_hi:[1,0,1]
	v_pk_fma_f32 v[20:21], v[84:85], v[28:29], v[20:21] op_sel_hi:[1,0,1] neg_lo:[0,1,0] neg_hi:[0,1,0]
	v_pk_fma_f32 v[22:23], v[86:87], v[28:29], v[22:23] op_sel_hi:[1,0,1] neg_lo:[0,1,0] neg_hi:[0,1,0]
	v_pk_fma_f32 v[24:25], v[84:85], v[30:31], v[24:25] op_sel_hi:[1,0,1] neg_lo:[0,1,0] neg_hi:[0,1,0]
	v_pk_fma_f32 v[26:27], v[86:87], v[30:31], v[26:27] op_sel_hi:[1,0,1] neg_lo:[0,1,0] neg_hi:[0,1,0]
	v_add_f32_e32 v39, v32, v5
	ds_write_b32 v102, v39 offset:512
	ds_read_b128 v[140:143], v195 offset:1536
	ds_read_b128 v[152:155], v195 offset:9728
	ds_read_b128 v[164:167], v195 offset:26112
	ds_read_b128 v[176:179], v195 offset:17920
	ds_read_b128 v[84:87], v195 offset:34304
	ds_read_b64 v[4:5], v196 offset:3072
	ds_read_b64 v[6:7], v36 offset:3072
	s_waitcnt lgkmcnt(8)
	v_pk_mul_f32 v[46:47], v[24:25], v[144:145] op_sel_hi:[0,1]
	v_pk_mul_f32 v[34:35], v[20:21], v[144:145] op_sel_hi:[0,1]
	v_pk_fma_f32 v[46:47], v[24:25], v[146:147], v[46:47] op_sel:[1,0,0] op_sel_hi:[1,1,1]
	v_pk_fma_f32 v[34:35], v[20:21], v[146:147], v[34:35] op_sel:[1,0,0] op_sel_hi:[1,1,1]
	v_pk_fma_f32 v[46:47], v[26:27], v[156:157], v[46:47] op_sel_hi:[0,1,1]
	v_pk_fma_f32 v[34:35], v[22:23], v[156:157], v[34:35] op_sel_hi:[0,1,1]
	v_pk_fma_f32 v[46:47], v[26:27], v[158:159], v[46:47] op_sel:[1,0,0] op_sel_hi:[1,1,1]
	v_pk_fma_f32 v[34:35], v[22:23], v[158:159], v[34:35] op_sel:[1,0,0] op_sel_hi:[1,1,1]
	v_pk_mul_f32 v[20:21], v[20:21], v[168:169]
	v_add_f32_dpp v28, v46, v34 row_half_mirror row_mask:0xf bank_mask:0xf
	v_add_f32_dpp v32, v47, v35 row_half_mirror row_mask:0xf bank_mask:0xf
	v_pk_mul_f32 v[22:23], v[22:23], v[170:171]
	v_add_f32_dpp v28, v28, v28 row_ror:8 row_mask:0xf bank_mask:0xf
	v_add_f32_dpp v32, v32, v32 row_ror:8 row_mask:0xf bank_mask:0xf
	v_pk_mul_f32 v[24:25], v[24:25], v[168:169]
	v_add_f32_dpp v28, v28, v28 quad_perm:[1,0,3,2] row_mask:0xf bank_mask:0xf
	v_add_f32_dpp v32, v32, v32 quad_perm:[1,0,3,2] row_mask:0xf bank_mask:0xf
	v_pk_mul_f32 v[26:27], v[26:27], v[170:171]
	v_add_f32_dpp v28, v28, v28 quad_perm:[2,3,0,1] row_mask:0xf bank_mask:0xf
	v_add_f32_dpp v32, v32, v32 quad_perm:[2,3,0,1] row_mask:0xf bank_mask:0xf
	v_pk_fma_f32 v[20:21], v[180:181], v[8:9], v[20:21] op_sel_hi:[1,0,1]
	v_mov_b32_dpp v30, v28 row_half_mirror row_mask:0xf bank_mask:0xf
	v_pk_fma_f32 v[22:23], v[182:183], v[8:9], v[22:23] op_sel_hi:[1,0,1]
	v_pk_fma_f32 v[24:25], v[180:181], v[10:11], v[24:25] op_sel_hi:[1,0,1]
	v_pk_fma_f32 v[26:27], v[182:183], v[10:11], v[26:27] op_sel_hi:[1,0,1]
	v_pk_fma_f32 v[20:21], v[88:89], v[28:29], v[20:21] op_sel_hi:[1,0,1] neg_lo:[0,1,0] neg_hi:[0,1,0]
	v_pk_fma_f32 v[22:23], v[90:91], v[28:29], v[22:23] op_sel_hi:[1,0,1] neg_lo:[0,1,0] neg_hi:[0,1,0]
	v_pk_fma_f32 v[24:25], v[88:89], v[30:31], v[24:25] op_sel_hi:[1,0,1] neg_lo:[0,1,0] neg_hi:[0,1,0]
	v_pk_fma_f32 v[26:27], v[90:91], v[30:31], v[26:27] op_sel_hi:[1,0,1] neg_lo:[0,1,0] neg_hi:[0,1,0]
	v_add_f32_e32 v39, v32, v9
	ds_write_b32 v102, v39 offset:640
	ds_read_b128 v[144:147], v195 offset:1792
	ds_read_b128 v[156:159], v195 offset:9984
	ds_read_b128 v[168:171], v195 offset:26368
	ds_read_b128 v[180:183], v195 offset:18176
	ds_read_b128 v[88:91], v195 offset:34560
	ds_read_b64 v[8:9], v196 offset:3584
	ds_read_b64 v[10:11], v36 offset:3584
	s_waitcnt lgkmcnt(8)
	v_pk_mul_f32 v[46:47], v[24:25], v[140:141] op_sel_hi:[0,1]
	v_pk_mul_f32 v[34:35], v[20:21], v[140:141] op_sel_hi:[0,1]
	v_pk_fma_f32 v[46:47], v[24:25], v[142:143], v[46:47] op_sel:[1,0,0] op_sel_hi:[1,1,1]
	v_pk_fma_f32 v[34:35], v[20:21], v[142:143], v[34:35] op_sel:[1,0,0] op_sel_hi:[1,1,1]
	v_pk_fma_f32 v[46:47], v[26:27], v[152:153], v[46:47] op_sel_hi:[0,1,1]
	v_pk_fma_f32 v[34:35], v[22:23], v[152:153], v[34:35] op_sel_hi:[0,1,1]
	v_pk_fma_f32 v[46:47], v[26:27], v[154:155], v[46:47] op_sel:[1,0,0] op_sel_hi:[1,1,1]
	v_pk_fma_f32 v[34:35], v[22:23], v[154:155], v[34:35] op_sel:[1,0,0] op_sel_hi:[1,1,1]
	v_pk_mul_f32 v[20:21], v[20:21], v[164:165]
	v_add_f32_dpp v28, v46, v34 row_half_mirror row_mask:0xf bank_mask:0xf
	v_add_f32_dpp v32, v47, v35 row_half_mirror row_mask:0xf bank_mask:0xf
	v_pk_mul_f32 v[22:23], v[22:23], v[166:167]
	v_add_f32_dpp v28, v28, v28 row_ror:8 row_mask:0xf bank_mask:0xf
	v_add_f32_dpp v32, v32, v32 row_ror:8 row_mask:0xf bank_mask:0xf
	v_pk_mul_f32 v[24:25], v[24:25], v[164:165]
	v_add_f32_dpp v28, v28, v28 quad_perm:[1,0,3,2] row_mask:0xf bank_mask:0xf
	v_add_f32_dpp v32, v32, v32 quad_perm:[1,0,3,2] row_mask:0xf bank_mask:0xf
	v_pk_mul_f32 v[26:27], v[26:27], v[166:167]
	v_add_f32_dpp v28, v28, v28 quad_perm:[2,3,0,1] row_mask:0xf bank_mask:0xf
	v_add_f32_dpp v32, v32, v32 quad_perm:[2,3,0,1] row_mask:0xf bank_mask:0xf
	v_pk_fma_f32 v[20:21], v[176:177], v[4:5], v[20:21] op_sel_hi:[1,0,1]
	v_mov_b32_dpp v30, v28 row_half_mirror row_mask:0xf bank_mask:0xf
	v_pk_fma_f32 v[22:23], v[178:179], v[4:5], v[22:23] op_sel_hi:[1,0,1]
	v_pk_fma_f32 v[24:25], v[176:177], v[6:7], v[24:25] op_sel_hi:[1,0,1]
	v_pk_fma_f32 v[26:27], v[178:179], v[6:7], v[26:27] op_sel_hi:[1,0,1]
	v_pk_fma_f32 v[20:21], v[84:85], v[28:29], v[20:21] op_sel_hi:[1,0,1] neg_lo:[0,1,0] neg_hi:[0,1,0]
	v_pk_fma_f32 v[22:23], v[86:87], v[28:29], v[22:23] op_sel_hi:[1,0,1] neg_lo:[0,1,0] neg_hi:[0,1,0]
	v_pk_fma_f32 v[24:25], v[84:85], v[30:31], v[24:25] op_sel_hi:[1,0,1] neg_lo:[0,1,0] neg_hi:[0,1,0]
	v_pk_fma_f32 v[26:27], v[86:87], v[30:31], v[26:27] op_sel_hi:[1,0,1] neg_lo:[0,1,0] neg_hi:[0,1,0]
	v_add_f32_e32 v39, v32, v5
	ds_write_b32 v102, v39 offset:768
	ds_read_b128 v[140:143], v195 offset:2048
	ds_read_b128 v[152:155], v195 offset:10240
	ds_read_b128 v[164:167], v195 offset:26624
	ds_read_b128 v[176:179], v195 offset:18432
	ds_read_b128 v[84:87], v195 offset:34816
	ds_read_b64 v[4:5], v196 offset:4096
	ds_read_b64 v[6:7], v36 offset:4096
	s_waitcnt lgkmcnt(8)
	v_pk_mul_f32 v[46:47], v[24:25], v[144:145] op_sel_hi:[0,1]
	v_pk_mul_f32 v[34:35], v[20:21], v[144:145] op_sel_hi:[0,1]
	v_pk_fma_f32 v[46:47], v[24:25], v[146:147], v[46:47] op_sel:[1,0,0] op_sel_hi:[1,1,1]
	v_pk_fma_f32 v[34:35], v[20:21], v[146:147], v[34:35] op_sel:[1,0,0] op_sel_hi:[1,1,1]
	v_pk_fma_f32 v[46:47], v[26:27], v[156:157], v[46:47] op_sel_hi:[0,1,1]
	v_pk_fma_f32 v[34:35], v[22:23], v[156:157], v[34:35] op_sel_hi:[0,1,1]
	v_pk_fma_f32 v[46:47], v[26:27], v[158:159], v[46:47] op_sel:[1,0,0] op_sel_hi:[1,1,1]
	v_pk_fma_f32 v[34:35], v[22:23], v[158:159], v[34:35] op_sel:[1,0,0] op_sel_hi:[1,1,1]
	v_pk_mul_f32 v[20:21], v[20:21], v[168:169]
	v_add_f32_dpp v28, v46, v34 row_half_mirror row_mask:0xf bank_mask:0xf
	v_add_f32_dpp v32, v47, v35 row_half_mirror row_mask:0xf bank_mask:0xf
	v_pk_mul_f32 v[22:23], v[22:23], v[170:171]
	v_add_f32_dpp v28, v28, v28 row_ror:8 row_mask:0xf bank_mask:0xf
	v_add_f32_dpp v32, v32, v32 row_ror:8 row_mask:0xf bank_mask:0xf
	v_pk_mul_f32 v[24:25], v[24:25], v[168:169]
	v_add_f32_dpp v28, v28, v28 quad_perm:[1,0,3,2] row_mask:0xf bank_mask:0xf
	v_add_f32_dpp v32, v32, v32 quad_perm:[1,0,3,2] row_mask:0xf bank_mask:0xf
	v_pk_mul_f32 v[26:27], v[26:27], v[170:171]
	v_add_f32_dpp v28, v28, v28 quad_perm:[2,3,0,1] row_mask:0xf bank_mask:0xf
	v_add_f32_dpp v32, v32, v32 quad_perm:[2,3,0,1] row_mask:0xf bank_mask:0xf
	v_pk_fma_f32 v[20:21], v[180:181], v[8:9], v[20:21] op_sel_hi:[1,0,1]
	v_mov_b32_dpp v30, v28 row_half_mirror row_mask:0xf bank_mask:0xf
	v_pk_fma_f32 v[22:23], v[182:183], v[8:9], v[22:23] op_sel_hi:[1,0,1]
	v_pk_fma_f32 v[24:25], v[180:181], v[10:11], v[24:25] op_sel_hi:[1,0,1]
	v_pk_fma_f32 v[26:27], v[182:183], v[10:11], v[26:27] op_sel_hi:[1,0,1]
	v_pk_fma_f32 v[20:21], v[88:89], v[28:29], v[20:21] op_sel_hi:[1,0,1] neg_lo:[0,1,0] neg_hi:[0,1,0]
	v_pk_fma_f32 v[22:23], v[90:91], v[28:29], v[22:23] op_sel_hi:[1,0,1] neg_lo:[0,1,0] neg_hi:[0,1,0]
	v_pk_fma_f32 v[24:25], v[88:89], v[30:31], v[24:25] op_sel_hi:[1,0,1] neg_lo:[0,1,0] neg_hi:[0,1,0]
	v_pk_fma_f32 v[26:27], v[90:91], v[30:31], v[26:27] op_sel_hi:[1,0,1] neg_lo:[0,1,0] neg_hi:[0,1,0]
	v_add_f32_e32 v39, v32, v9
	ds_write_b32 v102, v39 offset:896
	ds_read_b128 v[144:147], v195 offset:2304
	ds_read_b128 v[156:159], v195 offset:10496
	ds_read_b128 v[168:171], v195 offset:26880
	ds_read_b128 v[180:183], v195 offset:18688
	ds_read_b128 v[88:91], v195 offset:35072
	ds_read_b64 v[8:9], v196 offset:4608
	ds_read_b64 v[10:11], v36 offset:4608
	s_waitcnt lgkmcnt(8)
	v_pk_mul_f32 v[46:47], v[24:25], v[140:141] op_sel_hi:[0,1]
	v_pk_mul_f32 v[34:35], v[20:21], v[140:141] op_sel_hi:[0,1]
	v_pk_fma_f32 v[46:47], v[24:25], v[142:143], v[46:47] op_sel:[1,0,0] op_sel_hi:[1,1,1]
	v_pk_fma_f32 v[34:35], v[20:21], v[142:143], v[34:35] op_sel:[1,0,0] op_sel_hi:[1,1,1]
	v_pk_fma_f32 v[46:47], v[26:27], v[152:153], v[46:47] op_sel_hi:[0,1,1]
	v_pk_fma_f32 v[34:35], v[22:23], v[152:153], v[34:35] op_sel_hi:[0,1,1]
	v_pk_fma_f32 v[46:47], v[26:27], v[154:155], v[46:47] op_sel:[1,0,0] op_sel_hi:[1,1,1]
	v_pk_fma_f32 v[34:35], v[22:23], v[154:155], v[34:35] op_sel:[1,0,0] op_sel_hi:[1,1,1]
	v_pk_mul_f32 v[20:21], v[20:21], v[164:165]
	v_add_f32_dpp v28, v46, v34 row_half_mirror row_mask:0xf bank_mask:0xf
	v_add_f32_dpp v32, v47, v35 row_half_mirror row_mask:0xf bank_mask:0xf
	v_pk_mul_f32 v[22:23], v[22:23], v[166:167]
	v_add_f32_dpp v28, v28, v28 row_ror:8 row_mask:0xf bank_mask:0xf
	v_add_f32_dpp v32, v32, v32 row_ror:8 row_mask:0xf bank_mask:0xf
	v_pk_mul_f32 v[24:25], v[24:25], v[164:165]
	v_add_f32_dpp v28, v28, v28 quad_perm:[1,0,3,2] row_mask:0xf bank_mask:0xf
	v_add_f32_dpp v32, v32, v32 quad_perm:[1,0,3,2] row_mask:0xf bank_mask:0xf
	v_pk_mul_f32 v[26:27], v[26:27], v[166:167]
	v_add_f32_dpp v28, v28, v28 quad_perm:[2,3,0,1] row_mask:0xf bank_mask:0xf
	v_add_f32_dpp v32, v32, v32 quad_perm:[2,3,0,1] row_mask:0xf bank_mask:0xf
	v_pk_fma_f32 v[20:21], v[176:177], v[4:5], v[20:21] op_sel_hi:[1,0,1]
	v_mov_b32_dpp v30, v28 row_half_mirror row_mask:0xf bank_mask:0xf
	v_pk_fma_f32 v[22:23], v[178:179], v[4:5], v[22:23] op_sel_hi:[1,0,1]
	v_pk_fma_f32 v[24:25], v[176:177], v[6:7], v[24:25] op_sel_hi:[1,0,1]
	v_pk_fma_f32 v[26:27], v[178:179], v[6:7], v[26:27] op_sel_hi:[1,0,1]
	v_pk_fma_f32 v[20:21], v[84:85], v[28:29], v[20:21] op_sel_hi:[1,0,1] neg_lo:[0,1,0] neg_hi:[0,1,0]
	v_pk_fma_f32 v[22:23], v[86:87], v[28:29], v[22:23] op_sel_hi:[1,0,1] neg_lo:[0,1,0] neg_hi:[0,1,0]
	v_pk_fma_f32 v[24:25], v[84:85], v[30:31], v[24:25] op_sel_hi:[1,0,1] neg_lo:[0,1,0] neg_hi:[0,1,0]
	v_pk_fma_f32 v[26:27], v[86:87], v[30:31], v[26:27] op_sel_hi:[1,0,1] neg_lo:[0,1,0] neg_hi:[0,1,0]
	v_add_f32_e32 v39, v32, v5
	ds_write_b32 v102, v39 offset:1024
	ds_read_b128 v[140:143], v195 offset:2560
	ds_read_b128 v[152:155], v195 offset:10752
	ds_read_b128 v[164:167], v195 offset:27136
	ds_read_b128 v[176:179], v195 offset:18944
	ds_read_b128 v[84:87], v195 offset:35328
	ds_read_b64 v[4:5], v196 offset:5120
	ds_read_b64 v[6:7], v36 offset:5120
	s_waitcnt lgkmcnt(8)
	v_pk_mul_f32 v[46:47], v[24:25], v[144:145] op_sel_hi:[0,1]
	v_pk_mul_f32 v[34:35], v[20:21], v[144:145] op_sel_hi:[0,1]
	v_pk_fma_f32 v[46:47], v[24:25], v[146:147], v[46:47] op_sel:[1,0,0] op_sel_hi:[1,1,1]
	v_pk_fma_f32 v[34:35], v[20:21], v[146:147], v[34:35] op_sel:[1,0,0] op_sel_hi:[1,1,1]
	v_pk_fma_f32 v[46:47], v[26:27], v[156:157], v[46:47] op_sel_hi:[0,1,1]
	v_pk_fma_f32 v[34:35], v[22:23], v[156:157], v[34:35] op_sel_hi:[0,1,1]
	v_pk_fma_f32 v[46:47], v[26:27], v[158:159], v[46:47] op_sel:[1,0,0] op_sel_hi:[1,1,1]
	v_pk_fma_f32 v[34:35], v[22:23], v[158:159], v[34:35] op_sel:[1,0,0] op_sel_hi:[1,1,1]
	v_pk_mul_f32 v[20:21], v[20:21], v[168:169]
	v_add_f32_dpp v28, v46, v34 row_half_mirror row_mask:0xf bank_mask:0xf
	v_add_f32_dpp v32, v47, v35 row_half_mirror row_mask:0xf bank_mask:0xf
	v_pk_mul_f32 v[22:23], v[22:23], v[170:171]
	v_add_f32_dpp v28, v28, v28 row_ror:8 row_mask:0xf bank_mask:0xf
	v_add_f32_dpp v32, v32, v32 row_ror:8 row_mask:0xf bank_mask:0xf
	v_pk_mul_f32 v[24:25], v[24:25], v[168:169]
	v_add_f32_dpp v28, v28, v28 quad_perm:[1,0,3,2] row_mask:0xf bank_mask:0xf
	v_add_f32_dpp v32, v32, v32 quad_perm:[1,0,3,2] row_mask:0xf bank_mask:0xf
	v_pk_mul_f32 v[26:27], v[26:27], v[170:171]
	v_add_f32_dpp v28, v28, v28 quad_perm:[2,3,0,1] row_mask:0xf bank_mask:0xf
	v_add_f32_dpp v32, v32, v32 quad_perm:[2,3,0,1] row_mask:0xf bank_mask:0xf
	v_pk_fma_f32 v[20:21], v[180:181], v[8:9], v[20:21] op_sel_hi:[1,0,1]
	v_mov_b32_dpp v30, v28 row_half_mirror row_mask:0xf bank_mask:0xf
	v_pk_fma_f32 v[22:23], v[182:183], v[8:9], v[22:23] op_sel_hi:[1,0,1]
	v_pk_fma_f32 v[24:25], v[180:181], v[10:11], v[24:25] op_sel_hi:[1,0,1]
	v_pk_fma_f32 v[26:27], v[182:183], v[10:11], v[26:27] op_sel_hi:[1,0,1]
	v_pk_fma_f32 v[20:21], v[88:89], v[28:29], v[20:21] op_sel_hi:[1,0,1] neg_lo:[0,1,0] neg_hi:[0,1,0]
	v_pk_fma_f32 v[22:23], v[90:91], v[28:29], v[22:23] op_sel_hi:[1,0,1] neg_lo:[0,1,0] neg_hi:[0,1,0]
	v_pk_fma_f32 v[24:25], v[88:89], v[30:31], v[24:25] op_sel_hi:[1,0,1] neg_lo:[0,1,0] neg_hi:[0,1,0]
	v_pk_fma_f32 v[26:27], v[90:91], v[30:31], v[26:27] op_sel_hi:[1,0,1] neg_lo:[0,1,0] neg_hi:[0,1,0]
	v_add_f32_e32 v39, v32, v9
	ds_write_b32 v102, v39 offset:1152
	ds_read_b128 v[144:147], v195 offset:2816
	ds_read_b128 v[156:159], v195 offset:11008
	ds_read_b128 v[168:171], v195 offset:27392
	ds_read_b128 v[180:183], v195 offset:19200
	ds_read_b128 v[88:91], v195 offset:35584
	ds_read_b64 v[8:9], v196 offset:5632
	ds_read_b64 v[10:11], v36 offset:5632
	s_waitcnt lgkmcnt(8)
	v_pk_mul_f32 v[46:47], v[24:25], v[140:141] op_sel_hi:[0,1]
	v_pk_mul_f32 v[34:35], v[20:21], v[140:141] op_sel_hi:[0,1]
	v_pk_fma_f32 v[46:47], v[24:25], v[142:143], v[46:47] op_sel:[1,0,0] op_sel_hi:[1,1,1]
	v_pk_fma_f32 v[34:35], v[20:21], v[142:143], v[34:35] op_sel:[1,0,0] op_sel_hi:[1,1,1]
	v_pk_fma_f32 v[46:47], v[26:27], v[152:153], v[46:47] op_sel_hi:[0,1,1]
	v_pk_fma_f32 v[34:35], v[22:23], v[152:153], v[34:35] op_sel_hi:[0,1,1]
	v_pk_fma_f32 v[46:47], v[26:27], v[154:155], v[46:47] op_sel:[1,0,0] op_sel_hi:[1,1,1]
	v_pk_fma_f32 v[34:35], v[22:23], v[154:155], v[34:35] op_sel:[1,0,0] op_sel_hi:[1,1,1]
	v_pk_mul_f32 v[20:21], v[20:21], v[164:165]
	v_add_f32_dpp v28, v46, v34 row_half_mirror row_mask:0xf bank_mask:0xf
	v_add_f32_dpp v32, v47, v35 row_half_mirror row_mask:0xf bank_mask:0xf
	v_pk_mul_f32 v[22:23], v[22:23], v[166:167]
	v_add_f32_dpp v28, v28, v28 row_ror:8 row_mask:0xf bank_mask:0xf
	v_add_f32_dpp v32, v32, v32 row_ror:8 row_mask:0xf bank_mask:0xf
	v_pk_mul_f32 v[24:25], v[24:25], v[164:165]
	v_add_f32_dpp v28, v28, v28 quad_perm:[1,0,3,2] row_mask:0xf bank_mask:0xf
	v_add_f32_dpp v32, v32, v32 quad_perm:[1,0,3,2] row_mask:0xf bank_mask:0xf
	v_pk_mul_f32 v[26:27], v[26:27], v[166:167]
	v_add_f32_dpp v28, v28, v28 quad_perm:[2,3,0,1] row_mask:0xf bank_mask:0xf
	v_add_f32_dpp v32, v32, v32 quad_perm:[2,3,0,1] row_mask:0xf bank_mask:0xf
	v_pk_fma_f32 v[20:21], v[176:177], v[4:5], v[20:21] op_sel_hi:[1,0,1]
	v_mov_b32_dpp v30, v28 row_half_mirror row_mask:0xf bank_mask:0xf
	v_pk_fma_f32 v[22:23], v[178:179], v[4:5], v[22:23] op_sel_hi:[1,0,1]
	v_pk_fma_f32 v[24:25], v[176:177], v[6:7], v[24:25] op_sel_hi:[1,0,1]
	v_pk_fma_f32 v[26:27], v[178:179], v[6:7], v[26:27] op_sel_hi:[1,0,1]
	v_pk_fma_f32 v[20:21], v[84:85], v[28:29], v[20:21] op_sel_hi:[1,0,1] neg_lo:[0,1,0] neg_hi:[0,1,0]
	v_pk_fma_f32 v[22:23], v[86:87], v[28:29], v[22:23] op_sel_hi:[1,0,1] neg_lo:[0,1,0] neg_hi:[0,1,0]
	v_pk_fma_f32 v[24:25], v[84:85], v[30:31], v[24:25] op_sel_hi:[1,0,1] neg_lo:[0,1,0] neg_hi:[0,1,0]
	v_pk_fma_f32 v[26:27], v[86:87], v[30:31], v[26:27] op_sel_hi:[1,0,1] neg_lo:[0,1,0] neg_hi:[0,1,0]
	v_add_f32_e32 v39, v32, v5
	ds_write_b32 v102, v39 offset:1280
	ds_read_b128 v[140:143], v195 offset:3072
	ds_read_b128 v[152:155], v195 offset:11264
	ds_read_b128 v[164:167], v195 offset:27648
	ds_read_b128 v[176:179], v195 offset:19456
	ds_read_b128 v[84:87], v195 offset:35840
	ds_read_b64 v[4:5], v196 offset:6144
	ds_read_b64 v[6:7], v36 offset:6144
	s_waitcnt lgkmcnt(8)
	v_pk_mul_f32 v[46:47], v[24:25], v[144:145] op_sel_hi:[0,1]
	v_pk_mul_f32 v[34:35], v[20:21], v[144:145] op_sel_hi:[0,1]
	v_pk_fma_f32 v[46:47], v[24:25], v[146:147], v[46:47] op_sel:[1,0,0] op_sel_hi:[1,1,1]
	v_pk_fma_f32 v[34:35], v[20:21], v[146:147], v[34:35] op_sel:[1,0,0] op_sel_hi:[1,1,1]
	v_pk_fma_f32 v[46:47], v[26:27], v[156:157], v[46:47] op_sel_hi:[0,1,1]
	v_pk_fma_f32 v[34:35], v[22:23], v[156:157], v[34:35] op_sel_hi:[0,1,1]
	v_pk_fma_f32 v[46:47], v[26:27], v[158:159], v[46:47] op_sel:[1,0,0] op_sel_hi:[1,1,1]
	v_pk_fma_f32 v[34:35], v[22:23], v[158:159], v[34:35] op_sel:[1,0,0] op_sel_hi:[1,1,1]
	v_pk_mul_f32 v[20:21], v[20:21], v[168:169]
	v_add_f32_dpp v28, v46, v34 row_half_mirror row_mask:0xf bank_mask:0xf
	v_add_f32_dpp v32, v47, v35 row_half_mirror row_mask:0xf bank_mask:0xf
	v_pk_mul_f32 v[22:23], v[22:23], v[170:171]
	v_add_f32_dpp v28, v28, v28 row_ror:8 row_mask:0xf bank_mask:0xf
	v_add_f32_dpp v32, v32, v32 row_ror:8 row_mask:0xf bank_mask:0xf
	v_pk_mul_f32 v[24:25], v[24:25], v[168:169]
	v_add_f32_dpp v28, v28, v28 quad_perm:[1,0,3,2] row_mask:0xf bank_mask:0xf
	v_add_f32_dpp v32, v32, v32 quad_perm:[1,0,3,2] row_mask:0xf bank_mask:0xf
	v_pk_mul_f32 v[26:27], v[26:27], v[170:171]
	v_add_f32_dpp v28, v28, v28 quad_perm:[2,3,0,1] row_mask:0xf bank_mask:0xf
	v_add_f32_dpp v32, v32, v32 quad_perm:[2,3,0,1] row_mask:0xf bank_mask:0xf
	v_pk_fma_f32 v[20:21], v[180:181], v[8:9], v[20:21] op_sel_hi:[1,0,1]
	v_mov_b32_dpp v30, v28 row_half_mirror row_mask:0xf bank_mask:0xf
	v_pk_fma_f32 v[22:23], v[182:183], v[8:9], v[22:23] op_sel_hi:[1,0,1]
	v_pk_fma_f32 v[24:25], v[180:181], v[10:11], v[24:25] op_sel_hi:[1,0,1]
	v_pk_fma_f32 v[26:27], v[182:183], v[10:11], v[26:27] op_sel_hi:[1,0,1]
	v_pk_fma_f32 v[20:21], v[88:89], v[28:29], v[20:21] op_sel_hi:[1,0,1] neg_lo:[0,1,0] neg_hi:[0,1,0]
	v_pk_fma_f32 v[22:23], v[90:91], v[28:29], v[22:23] op_sel_hi:[1,0,1] neg_lo:[0,1,0] neg_hi:[0,1,0]
	v_pk_fma_f32 v[24:25], v[88:89], v[30:31], v[24:25] op_sel_hi:[1,0,1] neg_lo:[0,1,0] neg_hi:[0,1,0]
	v_pk_fma_f32 v[26:27], v[90:91], v[30:31], v[26:27] op_sel_hi:[1,0,1] neg_lo:[0,1,0] neg_hi:[0,1,0]
	v_add_f32_e32 v39, v32, v9
	ds_write_b32 v102, v39 offset:1408
	ds_read_b128 v[144:147], v195 offset:3328
	ds_read_b128 v[156:159], v195 offset:11520
	ds_read_b128 v[168:171], v195 offset:27904
	ds_read_b128 v[180:183], v195 offset:19712
	ds_read_b128 v[88:91], v195 offset:36096
	ds_read_b64 v[8:9], v196 offset:6656
	ds_read_b64 v[10:11], v36 offset:6656
	s_waitcnt lgkmcnt(8)
	v_pk_mul_f32 v[46:47], v[24:25], v[140:141] op_sel_hi:[0,1]
	v_pk_mul_f32 v[34:35], v[20:21], v[140:141] op_sel_hi:[0,1]
	v_pk_fma_f32 v[46:47], v[24:25], v[142:143], v[46:47] op_sel:[1,0,0] op_sel_hi:[1,1,1]
	v_pk_fma_f32 v[34:35], v[20:21], v[142:143], v[34:35] op_sel:[1,0,0] op_sel_hi:[1,1,1]
	v_pk_fma_f32 v[46:47], v[26:27], v[152:153], v[46:47] op_sel_hi:[0,1,1]
	v_pk_fma_f32 v[34:35], v[22:23], v[152:153], v[34:35] op_sel_hi:[0,1,1]
	v_pk_fma_f32 v[46:47], v[26:27], v[154:155], v[46:47] op_sel:[1,0,0] op_sel_hi:[1,1,1]
	v_pk_fma_f32 v[34:35], v[22:23], v[154:155], v[34:35] op_sel:[1,0,0] op_sel_hi:[1,1,1]
	v_pk_mul_f32 v[20:21], v[20:21], v[164:165]
	v_add_f32_dpp v28, v46, v34 row_half_mirror row_mask:0xf bank_mask:0xf
	v_add_f32_dpp v32, v47, v35 row_half_mirror row_mask:0xf bank_mask:0xf
	v_pk_mul_f32 v[22:23], v[22:23], v[166:167]
	v_add_f32_dpp v28, v28, v28 row_ror:8 row_mask:0xf bank_mask:0xf
	v_add_f32_dpp v32, v32, v32 row_ror:8 row_mask:0xf bank_mask:0xf
	v_pk_mul_f32 v[24:25], v[24:25], v[164:165]
	v_add_f32_dpp v28, v28, v28 quad_perm:[1,0,3,2] row_mask:0xf bank_mask:0xf
	v_add_f32_dpp v32, v32, v32 quad_perm:[1,0,3,2] row_mask:0xf bank_mask:0xf
	v_pk_mul_f32 v[26:27], v[26:27], v[166:167]
	v_add_f32_dpp v28, v28, v28 quad_perm:[2,3,0,1] row_mask:0xf bank_mask:0xf
	v_add_f32_dpp v32, v32, v32 quad_perm:[2,3,0,1] row_mask:0xf bank_mask:0xf
	v_pk_fma_f32 v[20:21], v[176:177], v[4:5], v[20:21] op_sel_hi:[1,0,1]
	v_mov_b32_dpp v30, v28 row_half_mirror row_mask:0xf bank_mask:0xf
	v_pk_fma_f32 v[22:23], v[178:179], v[4:5], v[22:23] op_sel_hi:[1,0,1]
	v_pk_fma_f32 v[24:25], v[176:177], v[6:7], v[24:25] op_sel_hi:[1,0,1]
	v_pk_fma_f32 v[26:27], v[178:179], v[6:7], v[26:27] op_sel_hi:[1,0,1]
	v_pk_fma_f32 v[20:21], v[84:85], v[28:29], v[20:21] op_sel_hi:[1,0,1] neg_lo:[0,1,0] neg_hi:[0,1,0]
	v_pk_fma_f32 v[22:23], v[86:87], v[28:29], v[22:23] op_sel_hi:[1,0,1] neg_lo:[0,1,0] neg_hi:[0,1,0]
	v_pk_fma_f32 v[24:25], v[84:85], v[30:31], v[24:25] op_sel_hi:[1,0,1] neg_lo:[0,1,0] neg_hi:[0,1,0]
	v_pk_fma_f32 v[26:27], v[86:87], v[30:31], v[26:27] op_sel_hi:[1,0,1] neg_lo:[0,1,0] neg_hi:[0,1,0]
	v_add_f32_e32 v39, v32, v5
	ds_write_b32 v102, v39 offset:1536
	ds_read_b128 v[140:143], v195 offset:3584
	ds_read_b128 v[152:155], v195 offset:11776
	ds_read_b128 v[164:167], v195 offset:28160
	ds_read_b128 v[176:179], v195 offset:19968
	ds_read_b128 v[84:87], v195 offset:36352
	ds_read_b64 v[4:5], v196 offset:7168
	ds_read_b64 v[6:7], v36 offset:7168
	s_waitcnt lgkmcnt(8)
	v_pk_mul_f32 v[46:47], v[24:25], v[144:145] op_sel_hi:[0,1]
	v_pk_mul_f32 v[34:35], v[20:21], v[144:145] op_sel_hi:[0,1]
	v_pk_fma_f32 v[46:47], v[24:25], v[146:147], v[46:47] op_sel:[1,0,0] op_sel_hi:[1,1,1]
	v_pk_fma_f32 v[34:35], v[20:21], v[146:147], v[34:35] op_sel:[1,0,0] op_sel_hi:[1,1,1]
	v_pk_fma_f32 v[46:47], v[26:27], v[156:157], v[46:47] op_sel_hi:[0,1,1]
	v_pk_fma_f32 v[34:35], v[22:23], v[156:157], v[34:35] op_sel_hi:[0,1,1]
	v_pk_fma_f32 v[46:47], v[26:27], v[158:159], v[46:47] op_sel:[1,0,0] op_sel_hi:[1,1,1]
	v_pk_fma_f32 v[34:35], v[22:23], v[158:159], v[34:35] op_sel:[1,0,0] op_sel_hi:[1,1,1]
	v_pk_mul_f32 v[20:21], v[20:21], v[168:169]
	v_add_f32_dpp v28, v46, v34 row_half_mirror row_mask:0xf bank_mask:0xf
	v_add_f32_dpp v32, v47, v35 row_half_mirror row_mask:0xf bank_mask:0xf
	v_pk_mul_f32 v[22:23], v[22:23], v[170:171]
	v_add_f32_dpp v28, v28, v28 row_ror:8 row_mask:0xf bank_mask:0xf
	v_add_f32_dpp v32, v32, v32 row_ror:8 row_mask:0xf bank_mask:0xf
	v_pk_mul_f32 v[24:25], v[24:25], v[168:169]
	v_add_f32_dpp v28, v28, v28 quad_perm:[1,0,3,2] row_mask:0xf bank_mask:0xf
	v_add_f32_dpp v32, v32, v32 quad_perm:[1,0,3,2] row_mask:0xf bank_mask:0xf
	v_pk_mul_f32 v[26:27], v[26:27], v[170:171]
	v_add_f32_dpp v28, v28, v28 quad_perm:[2,3,0,1] row_mask:0xf bank_mask:0xf
	v_add_f32_dpp v32, v32, v32 quad_perm:[2,3,0,1] row_mask:0xf bank_mask:0xf
	v_pk_fma_f32 v[20:21], v[180:181], v[8:9], v[20:21] op_sel_hi:[1,0,1]
	v_mov_b32_dpp v30, v28 row_half_mirror row_mask:0xf bank_mask:0xf
	v_pk_fma_f32 v[22:23], v[182:183], v[8:9], v[22:23] op_sel_hi:[1,0,1]
	v_pk_fma_f32 v[24:25], v[180:181], v[10:11], v[24:25] op_sel_hi:[1,0,1]
	v_pk_fma_f32 v[26:27], v[182:183], v[10:11], v[26:27] op_sel_hi:[1,0,1]
	v_pk_fma_f32 v[20:21], v[88:89], v[28:29], v[20:21] op_sel_hi:[1,0,1] neg_lo:[0,1,0] neg_hi:[0,1,0]
	v_pk_fma_f32 v[22:23], v[90:91], v[28:29], v[22:23] op_sel_hi:[1,0,1] neg_lo:[0,1,0] neg_hi:[0,1,0]
	v_pk_fma_f32 v[24:25], v[88:89], v[30:31], v[24:25] op_sel_hi:[1,0,1] neg_lo:[0,1,0] neg_hi:[0,1,0]
	v_pk_fma_f32 v[26:27], v[90:91], v[30:31], v[26:27] op_sel_hi:[1,0,1] neg_lo:[0,1,0] neg_hi:[0,1,0]
	v_add_f32_e32 v39, v32, v9
	ds_write_b32 v102, v39 offset:1664
	ds_read_b128 v[144:147], v195 offset:3840
	ds_read_b128 v[156:159], v195 offset:12032
	ds_read_b128 v[168:171], v195 offset:28416
	ds_read_b128 v[180:183], v195 offset:20224
	ds_read_b128 v[88:91], v195 offset:36608
	ds_read_b64 v[8:9], v196 offset:7680
	ds_read_b64 v[10:11], v36 offset:7680
	s_waitcnt lgkmcnt(8)
	v_pk_mul_f32 v[46:47], v[24:25], v[140:141] op_sel_hi:[0,1]
	v_pk_mul_f32 v[34:35], v[20:21], v[140:141] op_sel_hi:[0,1]
	v_pk_fma_f32 v[46:47], v[24:25], v[142:143], v[46:47] op_sel:[1,0,0] op_sel_hi:[1,1,1]
	v_pk_fma_f32 v[34:35], v[20:21], v[142:143], v[34:35] op_sel:[1,0,0] op_sel_hi:[1,1,1]
	v_pk_fma_f32 v[46:47], v[26:27], v[152:153], v[46:47] op_sel_hi:[0,1,1]
	v_pk_fma_f32 v[34:35], v[22:23], v[152:153], v[34:35] op_sel_hi:[0,1,1]
	v_pk_fma_f32 v[46:47], v[26:27], v[154:155], v[46:47] op_sel:[1,0,0] op_sel_hi:[1,1,1]
	v_pk_fma_f32 v[34:35], v[22:23], v[154:155], v[34:35] op_sel:[1,0,0] op_sel_hi:[1,1,1]
	v_pk_mul_f32 v[20:21], v[20:21], v[164:165]
	v_add_f32_dpp v28, v46, v34 row_half_mirror row_mask:0xf bank_mask:0xf
	v_add_f32_dpp v32, v47, v35 row_half_mirror row_mask:0xf bank_mask:0xf
	v_pk_mul_f32 v[22:23], v[22:23], v[166:167]
	v_add_f32_dpp v28, v28, v28 row_ror:8 row_mask:0xf bank_mask:0xf
	v_add_f32_dpp v32, v32, v32 row_ror:8 row_mask:0xf bank_mask:0xf
	v_pk_mul_f32 v[24:25], v[24:25], v[164:165]
	v_add_f32_dpp v28, v28, v28 quad_perm:[1,0,3,2] row_mask:0xf bank_mask:0xf
	v_add_f32_dpp v32, v32, v32 quad_perm:[1,0,3,2] row_mask:0xf bank_mask:0xf
	v_pk_mul_f32 v[26:27], v[26:27], v[166:167]
	v_add_f32_dpp v28, v28, v28 quad_perm:[2,3,0,1] row_mask:0xf bank_mask:0xf
	v_add_f32_dpp v32, v32, v32 quad_perm:[2,3,0,1] row_mask:0xf bank_mask:0xf
	v_pk_fma_f32 v[20:21], v[176:177], v[4:5], v[20:21] op_sel_hi:[1,0,1]
	v_mov_b32_dpp v30, v28 row_half_mirror row_mask:0xf bank_mask:0xf
	v_pk_fma_f32 v[22:23], v[178:179], v[4:5], v[22:23] op_sel_hi:[1,0,1]
	v_pk_fma_f32 v[24:25], v[176:177], v[6:7], v[24:25] op_sel_hi:[1,0,1]
	v_pk_fma_f32 v[26:27], v[178:179], v[6:7], v[26:27] op_sel_hi:[1,0,1]
	v_pk_fma_f32 v[20:21], v[84:85], v[28:29], v[20:21] op_sel_hi:[1,0,1] neg_lo:[0,1,0] neg_hi:[0,1,0]
	v_pk_fma_f32 v[22:23], v[86:87], v[28:29], v[22:23] op_sel_hi:[1,0,1] neg_lo:[0,1,0] neg_hi:[0,1,0]
	v_pk_fma_f32 v[24:25], v[84:85], v[30:31], v[24:25] op_sel_hi:[1,0,1] neg_lo:[0,1,0] neg_hi:[0,1,0]
	v_pk_fma_f32 v[26:27], v[86:87], v[30:31], v[26:27] op_sel_hi:[1,0,1] neg_lo:[0,1,0] neg_hi:[0,1,0]
	v_add_f32_e32 v39, v32, v5
	ds_write_b32 v102, v39 offset:1792
	ds_read_b128 v[140:143], v195 offset:4096
	ds_read_b128 v[152:155], v195 offset:12288
	ds_read_b128 v[164:167], v195 offset:28672
	ds_read_b128 v[176:179], v195 offset:20480
	ds_read_b128 v[84:87], v195 offset:36864
	ds_read_b64 v[4:5], v196 offset:8192
	ds_read_b64 v[6:7], v36 offset:8192
	s_waitcnt lgkmcnt(8)
	v_pk_mul_f32 v[46:47], v[24:25], v[144:145] op_sel_hi:[0,1]
	v_pk_mul_f32 v[34:35], v[20:21], v[144:145] op_sel_hi:[0,1]
	v_pk_fma_f32 v[46:47], v[24:25], v[146:147], v[46:47] op_sel:[1,0,0] op_sel_hi:[1,1,1]
	v_pk_fma_f32 v[34:35], v[20:21], v[146:147], v[34:35] op_sel:[1,0,0] op_sel_hi:[1,1,1]
	v_pk_fma_f32 v[46:47], v[26:27], v[156:157], v[46:47] op_sel_hi:[0,1,1]
	v_pk_fma_f32 v[34:35], v[22:23], v[156:157], v[34:35] op_sel_hi:[0,1,1]
	v_pk_fma_f32 v[46:47], v[26:27], v[158:159], v[46:47] op_sel:[1,0,0] op_sel_hi:[1,1,1]
	v_pk_fma_f32 v[34:35], v[22:23], v[158:159], v[34:35] op_sel:[1,0,0] op_sel_hi:[1,1,1]
	v_pk_mul_f32 v[20:21], v[20:21], v[168:169]
	v_add_f32_dpp v28, v46, v34 row_half_mirror row_mask:0xf bank_mask:0xf
	v_add_f32_dpp v32, v47, v35 row_half_mirror row_mask:0xf bank_mask:0xf
	v_pk_mul_f32 v[22:23], v[22:23], v[170:171]
	v_add_f32_dpp v28, v28, v28 row_ror:8 row_mask:0xf bank_mask:0xf
	v_add_f32_dpp v32, v32, v32 row_ror:8 row_mask:0xf bank_mask:0xf
	v_pk_mul_f32 v[24:25], v[24:25], v[168:169]
	v_add_f32_dpp v28, v28, v28 quad_perm:[1,0,3,2] row_mask:0xf bank_mask:0xf
	v_add_f32_dpp v32, v32, v32 quad_perm:[1,0,3,2] row_mask:0xf bank_mask:0xf
	v_pk_mul_f32 v[26:27], v[26:27], v[170:171]
	v_add_f32_dpp v28, v28, v28 quad_perm:[2,3,0,1] row_mask:0xf bank_mask:0xf
	v_add_f32_dpp v32, v32, v32 quad_perm:[2,3,0,1] row_mask:0xf bank_mask:0xf
	v_pk_fma_f32 v[20:21], v[180:181], v[8:9], v[20:21] op_sel_hi:[1,0,1]
	v_mov_b32_dpp v30, v28 row_half_mirror row_mask:0xf bank_mask:0xf
	v_pk_fma_f32 v[22:23], v[182:183], v[8:9], v[22:23] op_sel_hi:[1,0,1]
	v_pk_fma_f32 v[24:25], v[180:181], v[10:11], v[24:25] op_sel_hi:[1,0,1]
	v_pk_fma_f32 v[26:27], v[182:183], v[10:11], v[26:27] op_sel_hi:[1,0,1]
	v_pk_fma_f32 v[20:21], v[88:89], v[28:29], v[20:21] op_sel_hi:[1,0,1] neg_lo:[0,1,0] neg_hi:[0,1,0]
	v_pk_fma_f32 v[22:23], v[90:91], v[28:29], v[22:23] op_sel_hi:[1,0,1] neg_lo:[0,1,0] neg_hi:[0,1,0]
	v_pk_fma_f32 v[24:25], v[88:89], v[30:31], v[24:25] op_sel_hi:[1,0,1] neg_lo:[0,1,0] neg_hi:[0,1,0]
	v_pk_fma_f32 v[26:27], v[90:91], v[30:31], v[26:27] op_sel_hi:[1,0,1] neg_lo:[0,1,0] neg_hi:[0,1,0]
	v_add_f32_e32 v39, v32, v9
	ds_write_b32 v102, v39 offset:1920
	ds_read_b128 v[144:147], v195 offset:4352
	ds_read_b128 v[156:159], v195 offset:12544
	ds_read_b128 v[168:171], v195 offset:28928
	ds_read_b128 v[180:183], v195 offset:20736
	ds_read_b128 v[88:91], v195 offset:37120
	ds_read_b64 v[8:9], v196 offset:8704
	ds_read_b64 v[10:11], v36 offset:8704
	s_waitcnt lgkmcnt(8)
	v_pk_mul_f32 v[46:47], v[24:25], v[140:141] op_sel_hi:[0,1]
	v_pk_mul_f32 v[34:35], v[20:21], v[140:141] op_sel_hi:[0,1]
	v_pk_fma_f32 v[46:47], v[24:25], v[142:143], v[46:47] op_sel:[1,0,0] op_sel_hi:[1,1,1]
	v_pk_fma_f32 v[34:35], v[20:21], v[142:143], v[34:35] op_sel:[1,0,0] op_sel_hi:[1,1,1]
	v_pk_fma_f32 v[46:47], v[26:27], v[152:153], v[46:47] op_sel_hi:[0,1,1]
	v_pk_fma_f32 v[34:35], v[22:23], v[152:153], v[34:35] op_sel_hi:[0,1,1]
	v_pk_fma_f32 v[46:47], v[26:27], v[154:155], v[46:47] op_sel:[1,0,0] op_sel_hi:[1,1,1]
	v_pk_fma_f32 v[34:35], v[22:23], v[154:155], v[34:35] op_sel:[1,0,0] op_sel_hi:[1,1,1]
	v_pk_mul_f32 v[20:21], v[20:21], v[164:165]
	v_add_f32_dpp v28, v46, v34 row_half_mirror row_mask:0xf bank_mask:0xf
	v_add_f32_dpp v32, v47, v35 row_half_mirror row_mask:0xf bank_mask:0xf
	v_pk_mul_f32 v[22:23], v[22:23], v[166:167]
	v_add_f32_dpp v28, v28, v28 row_ror:8 row_mask:0xf bank_mask:0xf
	v_add_f32_dpp v32, v32, v32 row_ror:8 row_mask:0xf bank_mask:0xf
	v_pk_mul_f32 v[24:25], v[24:25], v[164:165]
	v_add_f32_dpp v28, v28, v28 quad_perm:[1,0,3,2] row_mask:0xf bank_mask:0xf
	v_add_f32_dpp v32, v32, v32 quad_perm:[1,0,3,2] row_mask:0xf bank_mask:0xf
	v_pk_mul_f32 v[26:27], v[26:27], v[166:167]
	v_add_f32_dpp v28, v28, v28 quad_perm:[2,3,0,1] row_mask:0xf bank_mask:0xf
	v_add_f32_dpp v32, v32, v32 quad_perm:[2,3,0,1] row_mask:0xf bank_mask:0xf
	v_pk_fma_f32 v[20:21], v[176:177], v[4:5], v[20:21] op_sel_hi:[1,0,1]
	v_mov_b32_dpp v30, v28 row_half_mirror row_mask:0xf bank_mask:0xf
	v_pk_fma_f32 v[22:23], v[178:179], v[4:5], v[22:23] op_sel_hi:[1,0,1]
	v_pk_fma_f32 v[24:25], v[176:177], v[6:7], v[24:25] op_sel_hi:[1,0,1]
	v_pk_fma_f32 v[26:27], v[178:179], v[6:7], v[26:27] op_sel_hi:[1,0,1]
	v_pk_fma_f32 v[20:21], v[84:85], v[28:29], v[20:21] op_sel_hi:[1,0,1] neg_lo:[0,1,0] neg_hi:[0,1,0]
	v_pk_fma_f32 v[22:23], v[86:87], v[28:29], v[22:23] op_sel_hi:[1,0,1] neg_lo:[0,1,0] neg_hi:[0,1,0]
	v_pk_fma_f32 v[24:25], v[84:85], v[30:31], v[24:25] op_sel_hi:[1,0,1] neg_lo:[0,1,0] neg_hi:[0,1,0]
	v_pk_fma_f32 v[26:27], v[86:87], v[30:31], v[26:27] op_sel_hi:[1,0,1] neg_lo:[0,1,0] neg_hi:[0,1,0]
	v_add_f32_e32 v39, v32, v5
	ds_write_b32 v102, v39 offset:2048
	ds_read_b128 v[140:143], v195 offset:4608
	ds_read_b128 v[152:155], v195 offset:12800
	ds_read_b128 v[164:167], v195 offset:29184
	ds_read_b128 v[176:179], v195 offset:20992
	ds_read_b128 v[84:87], v195 offset:37376
	ds_read_b64 v[4:5], v196 offset:9216
	ds_read_b64 v[6:7], v36 offset:9216
	s_waitcnt lgkmcnt(8)
	v_pk_mul_f32 v[46:47], v[24:25], v[144:145] op_sel_hi:[0,1]
	v_pk_mul_f32 v[34:35], v[20:21], v[144:145] op_sel_hi:[0,1]
	v_pk_fma_f32 v[46:47], v[24:25], v[146:147], v[46:47] op_sel:[1,0,0] op_sel_hi:[1,1,1]
	v_pk_fma_f32 v[34:35], v[20:21], v[146:147], v[34:35] op_sel:[1,0,0] op_sel_hi:[1,1,1]
	v_pk_fma_f32 v[46:47], v[26:27], v[156:157], v[46:47] op_sel_hi:[0,1,1]
	v_pk_fma_f32 v[34:35], v[22:23], v[156:157], v[34:35] op_sel_hi:[0,1,1]
	v_pk_fma_f32 v[46:47], v[26:27], v[158:159], v[46:47] op_sel:[1,0,0] op_sel_hi:[1,1,1]
	v_pk_fma_f32 v[34:35], v[22:23], v[158:159], v[34:35] op_sel:[1,0,0] op_sel_hi:[1,1,1]
	v_pk_mul_f32 v[20:21], v[20:21], v[168:169]
	v_add_f32_dpp v28, v46, v34 row_half_mirror row_mask:0xf bank_mask:0xf
	v_add_f32_dpp v32, v47, v35 row_half_mirror row_mask:0xf bank_mask:0xf
	v_pk_mul_f32 v[22:23], v[22:23], v[170:171]
	v_add_f32_dpp v28, v28, v28 row_ror:8 row_mask:0xf bank_mask:0xf
	v_add_f32_dpp v32, v32, v32 row_ror:8 row_mask:0xf bank_mask:0xf
	v_pk_mul_f32 v[24:25], v[24:25], v[168:169]
	v_add_f32_dpp v28, v28, v28 quad_perm:[1,0,3,2] row_mask:0xf bank_mask:0xf
	v_add_f32_dpp v32, v32, v32 quad_perm:[1,0,3,2] row_mask:0xf bank_mask:0xf
	v_pk_mul_f32 v[26:27], v[26:27], v[170:171]
	v_add_f32_dpp v28, v28, v28 quad_perm:[2,3,0,1] row_mask:0xf bank_mask:0xf
	v_add_f32_dpp v32, v32, v32 quad_perm:[2,3,0,1] row_mask:0xf bank_mask:0xf
	v_pk_fma_f32 v[20:21], v[180:181], v[8:9], v[20:21] op_sel_hi:[1,0,1]
	v_mov_b32_dpp v30, v28 row_half_mirror row_mask:0xf bank_mask:0xf
	v_pk_fma_f32 v[22:23], v[182:183], v[8:9], v[22:23] op_sel_hi:[1,0,1]
	v_pk_fma_f32 v[24:25], v[180:181], v[10:11], v[24:25] op_sel_hi:[1,0,1]
	v_pk_fma_f32 v[26:27], v[182:183], v[10:11], v[26:27] op_sel_hi:[1,0,1]
	v_pk_fma_f32 v[20:21], v[88:89], v[28:29], v[20:21] op_sel_hi:[1,0,1] neg_lo:[0,1,0] neg_hi:[0,1,0]
	v_pk_fma_f32 v[22:23], v[90:91], v[28:29], v[22:23] op_sel_hi:[1,0,1] neg_lo:[0,1,0] neg_hi:[0,1,0]
	v_pk_fma_f32 v[24:25], v[88:89], v[30:31], v[24:25] op_sel_hi:[1,0,1] neg_lo:[0,1,0] neg_hi:[0,1,0]
	v_pk_fma_f32 v[26:27], v[90:91], v[30:31], v[26:27] op_sel_hi:[1,0,1] neg_lo:[0,1,0] neg_hi:[0,1,0]
	v_add_f32_e32 v39, v32, v9
	ds_write_b32 v102, v39 offset:2176
	ds_read_b128 v[144:147], v195 offset:4864
	ds_read_b128 v[156:159], v195 offset:13056
	ds_read_b128 v[168:171], v195 offset:29440
	ds_read_b128 v[180:183], v195 offset:21248
	ds_read_b128 v[88:91], v195 offset:37632
	ds_read_b64 v[8:9], v196 offset:9728
	ds_read_b64 v[10:11], v36 offset:9728
	s_waitcnt lgkmcnt(8)
	v_pk_mul_f32 v[46:47], v[24:25], v[140:141] op_sel_hi:[0,1]
	v_pk_mul_f32 v[34:35], v[20:21], v[140:141] op_sel_hi:[0,1]
	v_pk_fma_f32 v[46:47], v[24:25], v[142:143], v[46:47] op_sel:[1,0,0] op_sel_hi:[1,1,1]
	v_pk_fma_f32 v[34:35], v[20:21], v[142:143], v[34:35] op_sel:[1,0,0] op_sel_hi:[1,1,1]
	v_pk_fma_f32 v[46:47], v[26:27], v[152:153], v[46:47] op_sel_hi:[0,1,1]
	v_pk_fma_f32 v[34:35], v[22:23], v[152:153], v[34:35] op_sel_hi:[0,1,1]
	v_pk_fma_f32 v[46:47], v[26:27], v[154:155], v[46:47] op_sel:[1,0,0] op_sel_hi:[1,1,1]
	v_pk_fma_f32 v[34:35], v[22:23], v[154:155], v[34:35] op_sel:[1,0,0] op_sel_hi:[1,1,1]
	v_pk_mul_f32 v[20:21], v[20:21], v[164:165]
	v_add_f32_dpp v28, v46, v34 row_half_mirror row_mask:0xf bank_mask:0xf
	v_add_f32_dpp v32, v47, v35 row_half_mirror row_mask:0xf bank_mask:0xf
	v_pk_mul_f32 v[22:23], v[22:23], v[166:167]
	v_add_f32_dpp v28, v28, v28 row_ror:8 row_mask:0xf bank_mask:0xf
	v_add_f32_dpp v32, v32, v32 row_ror:8 row_mask:0xf bank_mask:0xf
	v_pk_mul_f32 v[24:25], v[24:25], v[164:165]
	v_add_f32_dpp v28, v28, v28 quad_perm:[1,0,3,2] row_mask:0xf bank_mask:0xf
	v_add_f32_dpp v32, v32, v32 quad_perm:[1,0,3,2] row_mask:0xf bank_mask:0xf
	v_pk_mul_f32 v[26:27], v[26:27], v[166:167]
	v_add_f32_dpp v28, v28, v28 quad_perm:[2,3,0,1] row_mask:0xf bank_mask:0xf
	v_add_f32_dpp v32, v32, v32 quad_perm:[2,3,0,1] row_mask:0xf bank_mask:0xf
	v_pk_fma_f32 v[20:21], v[176:177], v[4:5], v[20:21] op_sel_hi:[1,0,1]
	v_mov_b32_dpp v30, v28 row_half_mirror row_mask:0xf bank_mask:0xf
	v_pk_fma_f32 v[22:23], v[178:179], v[4:5], v[22:23] op_sel_hi:[1,0,1]
	v_pk_fma_f32 v[24:25], v[176:177], v[6:7], v[24:25] op_sel_hi:[1,0,1]
	v_pk_fma_f32 v[26:27], v[178:179], v[6:7], v[26:27] op_sel_hi:[1,0,1]
	v_pk_fma_f32 v[20:21], v[84:85], v[28:29], v[20:21] op_sel_hi:[1,0,1] neg_lo:[0,1,0] neg_hi:[0,1,0]
	v_pk_fma_f32 v[22:23], v[86:87], v[28:29], v[22:23] op_sel_hi:[1,0,1] neg_lo:[0,1,0] neg_hi:[0,1,0]
	v_pk_fma_f32 v[24:25], v[84:85], v[30:31], v[24:25] op_sel_hi:[1,0,1] neg_lo:[0,1,0] neg_hi:[0,1,0]
	v_pk_fma_f32 v[26:27], v[86:87], v[30:31], v[26:27] op_sel_hi:[1,0,1] neg_lo:[0,1,0] neg_hi:[0,1,0]
	v_add_f32_e32 v39, v32, v5
	ds_write_b32 v102, v39 offset:2304
	ds_read_b128 v[140:143], v195 offset:5120
	ds_read_b128 v[152:155], v195 offset:13312
	ds_read_b128 v[164:167], v195 offset:29696
	ds_read_b128 v[176:179], v195 offset:21504
	ds_read_b128 v[84:87], v195 offset:37888
	ds_read_b64 v[4:5], v196 offset:10240
	ds_read_b64 v[6:7], v36 offset:10240
	s_waitcnt lgkmcnt(8)
	v_pk_mul_f32 v[46:47], v[24:25], v[144:145] op_sel_hi:[0,1]
	v_pk_mul_f32 v[34:35], v[20:21], v[144:145] op_sel_hi:[0,1]
	v_pk_fma_f32 v[46:47], v[24:25], v[146:147], v[46:47] op_sel:[1,0,0] op_sel_hi:[1,1,1]
	v_pk_fma_f32 v[34:35], v[20:21], v[146:147], v[34:35] op_sel:[1,0,0] op_sel_hi:[1,1,1]
	v_pk_fma_f32 v[46:47], v[26:27], v[156:157], v[46:47] op_sel_hi:[0,1,1]
	v_pk_fma_f32 v[34:35], v[22:23], v[156:157], v[34:35] op_sel_hi:[0,1,1]
	v_pk_fma_f32 v[46:47], v[26:27], v[158:159], v[46:47] op_sel:[1,0,0] op_sel_hi:[1,1,1]
	v_pk_fma_f32 v[34:35], v[22:23], v[158:159], v[34:35] op_sel:[1,0,0] op_sel_hi:[1,1,1]
	v_pk_mul_f32 v[20:21], v[20:21], v[168:169]
	v_add_f32_dpp v28, v46, v34 row_half_mirror row_mask:0xf bank_mask:0xf
	v_add_f32_dpp v32, v47, v35 row_half_mirror row_mask:0xf bank_mask:0xf
	v_pk_mul_f32 v[22:23], v[22:23], v[170:171]
	v_add_f32_dpp v28, v28, v28 row_ror:8 row_mask:0xf bank_mask:0xf
	v_add_f32_dpp v32, v32, v32 row_ror:8 row_mask:0xf bank_mask:0xf
	v_pk_mul_f32 v[24:25], v[24:25], v[168:169]
	v_add_f32_dpp v28, v28, v28 quad_perm:[1,0,3,2] row_mask:0xf bank_mask:0xf
	v_add_f32_dpp v32, v32, v32 quad_perm:[1,0,3,2] row_mask:0xf bank_mask:0xf
	v_pk_mul_f32 v[26:27], v[26:27], v[170:171]
	v_add_f32_dpp v28, v28, v28 quad_perm:[2,3,0,1] row_mask:0xf bank_mask:0xf
	v_add_f32_dpp v32, v32, v32 quad_perm:[2,3,0,1] row_mask:0xf bank_mask:0xf
	v_pk_fma_f32 v[20:21], v[180:181], v[8:9], v[20:21] op_sel_hi:[1,0,1]
	v_mov_b32_dpp v30, v28 row_half_mirror row_mask:0xf bank_mask:0xf
	v_pk_fma_f32 v[22:23], v[182:183], v[8:9], v[22:23] op_sel_hi:[1,0,1]
	v_pk_fma_f32 v[24:25], v[180:181], v[10:11], v[24:25] op_sel_hi:[1,0,1]
	v_pk_fma_f32 v[26:27], v[182:183], v[10:11], v[26:27] op_sel_hi:[1,0,1]
	v_pk_fma_f32 v[20:21], v[88:89], v[28:29], v[20:21] op_sel_hi:[1,0,1] neg_lo:[0,1,0] neg_hi:[0,1,0]
	v_pk_fma_f32 v[22:23], v[90:91], v[28:29], v[22:23] op_sel_hi:[1,0,1] neg_lo:[0,1,0] neg_hi:[0,1,0]
	v_pk_fma_f32 v[24:25], v[88:89], v[30:31], v[24:25] op_sel_hi:[1,0,1] neg_lo:[0,1,0] neg_hi:[0,1,0]
	v_pk_fma_f32 v[26:27], v[90:91], v[30:31], v[26:27] op_sel_hi:[1,0,1] neg_lo:[0,1,0] neg_hi:[0,1,0]
	v_add_f32_e32 v39, v32, v9
	ds_write_b32 v102, v39 offset:2432
	ds_read_b128 v[144:147], v195 offset:5376
	ds_read_b128 v[156:159], v195 offset:13568
	ds_read_b128 v[168:171], v195 offset:29952
	ds_read_b128 v[180:183], v195 offset:21760
	ds_read_b128 v[88:91], v195 offset:38144
	ds_read_b64 v[8:9], v196 offset:10752
	ds_read_b64 v[10:11], v36 offset:10752
	s_waitcnt lgkmcnt(8)
	v_pk_mul_f32 v[46:47], v[24:25], v[140:141] op_sel_hi:[0,1]
	v_pk_mul_f32 v[34:35], v[20:21], v[140:141] op_sel_hi:[0,1]
	v_pk_fma_f32 v[46:47], v[24:25], v[142:143], v[46:47] op_sel:[1,0,0] op_sel_hi:[1,1,1]
	v_pk_fma_f32 v[34:35], v[20:21], v[142:143], v[34:35] op_sel:[1,0,0] op_sel_hi:[1,1,1]
	v_pk_fma_f32 v[46:47], v[26:27], v[152:153], v[46:47] op_sel_hi:[0,1,1]
	v_pk_fma_f32 v[34:35], v[22:23], v[152:153], v[34:35] op_sel_hi:[0,1,1]
	v_pk_fma_f32 v[46:47], v[26:27], v[154:155], v[46:47] op_sel:[1,0,0] op_sel_hi:[1,1,1]
	v_pk_fma_f32 v[34:35], v[22:23], v[154:155], v[34:35] op_sel:[1,0,0] op_sel_hi:[1,1,1]
	v_pk_mul_f32 v[20:21], v[20:21], v[164:165]
	v_add_f32_dpp v28, v46, v34 row_half_mirror row_mask:0xf bank_mask:0xf
	v_add_f32_dpp v32, v47, v35 row_half_mirror row_mask:0xf bank_mask:0xf
	v_pk_mul_f32 v[22:23], v[22:23], v[166:167]
	v_add_f32_dpp v28, v28, v28 row_ror:8 row_mask:0xf bank_mask:0xf
	v_add_f32_dpp v32, v32, v32 row_ror:8 row_mask:0xf bank_mask:0xf
	v_pk_mul_f32 v[24:25], v[24:25], v[164:165]
	v_add_f32_dpp v28, v28, v28 quad_perm:[1,0,3,2] row_mask:0xf bank_mask:0xf
	v_add_f32_dpp v32, v32, v32 quad_perm:[1,0,3,2] row_mask:0xf bank_mask:0xf
	v_pk_mul_f32 v[26:27], v[26:27], v[166:167]
	v_add_f32_dpp v28, v28, v28 quad_perm:[2,3,0,1] row_mask:0xf bank_mask:0xf
	v_add_f32_dpp v32, v32, v32 quad_perm:[2,3,0,1] row_mask:0xf bank_mask:0xf
	v_pk_fma_f32 v[20:21], v[176:177], v[4:5], v[20:21] op_sel_hi:[1,0,1]
	v_mov_b32_dpp v30, v28 row_half_mirror row_mask:0xf bank_mask:0xf
	v_pk_fma_f32 v[22:23], v[178:179], v[4:5], v[22:23] op_sel_hi:[1,0,1]
	v_pk_fma_f32 v[24:25], v[176:177], v[6:7], v[24:25] op_sel_hi:[1,0,1]
	v_pk_fma_f32 v[26:27], v[178:179], v[6:7], v[26:27] op_sel_hi:[1,0,1]
	v_pk_fma_f32 v[20:21], v[84:85], v[28:29], v[20:21] op_sel_hi:[1,0,1] neg_lo:[0,1,0] neg_hi:[0,1,0]
	v_pk_fma_f32 v[22:23], v[86:87], v[28:29], v[22:23] op_sel_hi:[1,0,1] neg_lo:[0,1,0] neg_hi:[0,1,0]
	v_pk_fma_f32 v[24:25], v[84:85], v[30:31], v[24:25] op_sel_hi:[1,0,1] neg_lo:[0,1,0] neg_hi:[0,1,0]
	v_pk_fma_f32 v[26:27], v[86:87], v[30:31], v[26:27] op_sel_hi:[1,0,1] neg_lo:[0,1,0] neg_hi:[0,1,0]
	v_add_f32_e32 v39, v32, v5
	ds_write_b32 v102, v39 offset:2560
	ds_read_b128 v[140:143], v195 offset:5632
	ds_read_b128 v[152:155], v195 offset:13824
	ds_read_b128 v[164:167], v195 offset:30208
	ds_read_b128 v[176:179], v195 offset:22016
	ds_read_b128 v[84:87], v195 offset:38400
	ds_read_b64 v[4:5], v196 offset:11264
	ds_read_b64 v[6:7], v36 offset:11264
	s_waitcnt lgkmcnt(8)
	v_pk_mul_f32 v[46:47], v[24:25], v[144:145] op_sel_hi:[0,1]
	v_pk_mul_f32 v[34:35], v[20:21], v[144:145] op_sel_hi:[0,1]
	v_pk_fma_f32 v[46:47], v[24:25], v[146:147], v[46:47] op_sel:[1,0,0] op_sel_hi:[1,1,1]
	v_pk_fma_f32 v[34:35], v[20:21], v[146:147], v[34:35] op_sel:[1,0,0] op_sel_hi:[1,1,1]
	v_pk_fma_f32 v[46:47], v[26:27], v[156:157], v[46:47] op_sel_hi:[0,1,1]
	v_pk_fma_f32 v[34:35], v[22:23], v[156:157], v[34:35] op_sel_hi:[0,1,1]
	v_pk_fma_f32 v[46:47], v[26:27], v[158:159], v[46:47] op_sel:[1,0,0] op_sel_hi:[1,1,1]
	v_pk_fma_f32 v[34:35], v[22:23], v[158:159], v[34:35] op_sel:[1,0,0] op_sel_hi:[1,1,1]
	v_pk_mul_f32 v[20:21], v[20:21], v[168:169]
	v_add_f32_dpp v28, v46, v34 row_half_mirror row_mask:0xf bank_mask:0xf
	v_add_f32_dpp v32, v47, v35 row_half_mirror row_mask:0xf bank_mask:0xf
	v_pk_mul_f32 v[22:23], v[22:23], v[170:171]
	v_add_f32_dpp v28, v28, v28 row_ror:8 row_mask:0xf bank_mask:0xf
	v_add_f32_dpp v32, v32, v32 row_ror:8 row_mask:0xf bank_mask:0xf
	v_pk_mul_f32 v[24:25], v[24:25], v[168:169]
	v_add_f32_dpp v28, v28, v28 quad_perm:[1,0,3,2] row_mask:0xf bank_mask:0xf
	v_add_f32_dpp v32, v32, v32 quad_perm:[1,0,3,2] row_mask:0xf bank_mask:0xf
	v_pk_mul_f32 v[26:27], v[26:27], v[170:171]
	v_add_f32_dpp v28, v28, v28 quad_perm:[2,3,0,1] row_mask:0xf bank_mask:0xf
	v_add_f32_dpp v32, v32, v32 quad_perm:[2,3,0,1] row_mask:0xf bank_mask:0xf
	v_pk_fma_f32 v[20:21], v[180:181], v[8:9], v[20:21] op_sel_hi:[1,0,1]
	v_mov_b32_dpp v30, v28 row_half_mirror row_mask:0xf bank_mask:0xf
	v_pk_fma_f32 v[22:23], v[182:183], v[8:9], v[22:23] op_sel_hi:[1,0,1]
	v_pk_fma_f32 v[24:25], v[180:181], v[10:11], v[24:25] op_sel_hi:[1,0,1]
	v_pk_fma_f32 v[26:27], v[182:183], v[10:11], v[26:27] op_sel_hi:[1,0,1]
	v_pk_fma_f32 v[20:21], v[88:89], v[28:29], v[20:21] op_sel_hi:[1,0,1] neg_lo:[0,1,0] neg_hi:[0,1,0]
	v_pk_fma_f32 v[22:23], v[90:91], v[28:29], v[22:23] op_sel_hi:[1,0,1] neg_lo:[0,1,0] neg_hi:[0,1,0]
	v_pk_fma_f32 v[24:25], v[88:89], v[30:31], v[24:25] op_sel_hi:[1,0,1] neg_lo:[0,1,0] neg_hi:[0,1,0]
	v_pk_fma_f32 v[26:27], v[90:91], v[30:31], v[26:27] op_sel_hi:[1,0,1] neg_lo:[0,1,0] neg_hi:[0,1,0]
	v_add_f32_e32 v39, v32, v9
	ds_write_b32 v102, v39 offset:2688
	ds_read_b128 v[144:147], v195 offset:5888
	ds_read_b128 v[156:159], v195 offset:14080
	ds_read_b128 v[168:171], v195 offset:30464
	ds_read_b128 v[180:183], v195 offset:22272
	ds_read_b128 v[88:91], v195 offset:38656
	ds_read_b64 v[8:9], v196 offset:11776
	ds_read_b64 v[10:11], v36 offset:11776
	s_waitcnt lgkmcnt(8)
	v_pk_mul_f32 v[46:47], v[24:25], v[140:141] op_sel_hi:[0,1]
	v_pk_mul_f32 v[34:35], v[20:21], v[140:141] op_sel_hi:[0,1]
	v_pk_fma_f32 v[46:47], v[24:25], v[142:143], v[46:47] op_sel:[1,0,0] op_sel_hi:[1,1,1]
	v_pk_fma_f32 v[34:35], v[20:21], v[142:143], v[34:35] op_sel:[1,0,0] op_sel_hi:[1,1,1]
	v_pk_fma_f32 v[46:47], v[26:27], v[152:153], v[46:47] op_sel_hi:[0,1,1]
	v_pk_fma_f32 v[34:35], v[22:23], v[152:153], v[34:35] op_sel_hi:[0,1,1]
	v_pk_fma_f32 v[46:47], v[26:27], v[154:155], v[46:47] op_sel:[1,0,0] op_sel_hi:[1,1,1]
	v_pk_fma_f32 v[34:35], v[22:23], v[154:155], v[34:35] op_sel:[1,0,0] op_sel_hi:[1,1,1]
	v_pk_mul_f32 v[20:21], v[20:21], v[164:165]
	v_add_f32_dpp v28, v46, v34 row_half_mirror row_mask:0xf bank_mask:0xf
	v_add_f32_dpp v32, v47, v35 row_half_mirror row_mask:0xf bank_mask:0xf
	v_pk_mul_f32 v[22:23], v[22:23], v[166:167]
	v_add_f32_dpp v28, v28, v28 row_ror:8 row_mask:0xf bank_mask:0xf
	v_add_f32_dpp v32, v32, v32 row_ror:8 row_mask:0xf bank_mask:0xf
	v_pk_mul_f32 v[24:25], v[24:25], v[164:165]
	v_add_f32_dpp v28, v28, v28 quad_perm:[1,0,3,2] row_mask:0xf bank_mask:0xf
	v_add_f32_dpp v32, v32, v32 quad_perm:[1,0,3,2] row_mask:0xf bank_mask:0xf
	v_pk_mul_f32 v[26:27], v[26:27], v[166:167]
	v_add_f32_dpp v28, v28, v28 quad_perm:[2,3,0,1] row_mask:0xf bank_mask:0xf
	v_add_f32_dpp v32, v32, v32 quad_perm:[2,3,0,1] row_mask:0xf bank_mask:0xf
	v_pk_fma_f32 v[20:21], v[176:177], v[4:5], v[20:21] op_sel_hi:[1,0,1]
	v_mov_b32_dpp v30, v28 row_half_mirror row_mask:0xf bank_mask:0xf
	v_pk_fma_f32 v[22:23], v[178:179], v[4:5], v[22:23] op_sel_hi:[1,0,1]
	v_pk_fma_f32 v[24:25], v[176:177], v[6:7], v[24:25] op_sel_hi:[1,0,1]
	v_pk_fma_f32 v[26:27], v[178:179], v[6:7], v[26:27] op_sel_hi:[1,0,1]
	v_pk_fma_f32 v[20:21], v[84:85], v[28:29], v[20:21] op_sel_hi:[1,0,1] neg_lo:[0,1,0] neg_hi:[0,1,0]
	v_pk_fma_f32 v[22:23], v[86:87], v[28:29], v[22:23] op_sel_hi:[1,0,1] neg_lo:[0,1,0] neg_hi:[0,1,0]
	v_pk_fma_f32 v[24:25], v[84:85], v[30:31], v[24:25] op_sel_hi:[1,0,1] neg_lo:[0,1,0] neg_hi:[0,1,0]
	v_pk_fma_f32 v[26:27], v[86:87], v[30:31], v[26:27] op_sel_hi:[1,0,1] neg_lo:[0,1,0] neg_hi:[0,1,0]
	v_add_f32_e32 v39, v32, v5
	ds_write_b32 v102, v39 offset:2816
	ds_read_b128 v[140:143], v195 offset:6144
	ds_read_b128 v[152:155], v195 offset:14336
	ds_read_b128 v[164:167], v195 offset:30720
	ds_read_b128 v[176:179], v195 offset:22528
	ds_read_b128 v[84:87], v195 offset:38912
	ds_read_b64 v[4:5], v196 offset:12288
	ds_read_b64 v[6:7], v36 offset:12288
	s_waitcnt lgkmcnt(8)
	v_pk_mul_f32 v[46:47], v[24:25], v[144:145] op_sel_hi:[0,1]
	v_pk_mul_f32 v[34:35], v[20:21], v[144:145] op_sel_hi:[0,1]
	v_pk_fma_f32 v[46:47], v[24:25], v[146:147], v[46:47] op_sel:[1,0,0] op_sel_hi:[1,1,1]
	v_pk_fma_f32 v[34:35], v[20:21], v[146:147], v[34:35] op_sel:[1,0,0] op_sel_hi:[1,1,1]
	v_pk_fma_f32 v[46:47], v[26:27], v[156:157], v[46:47] op_sel_hi:[0,1,1]
	v_pk_fma_f32 v[34:35], v[22:23], v[156:157], v[34:35] op_sel_hi:[0,1,1]
	v_pk_fma_f32 v[46:47], v[26:27], v[158:159], v[46:47] op_sel:[1,0,0] op_sel_hi:[1,1,1]
	v_pk_fma_f32 v[34:35], v[22:23], v[158:159], v[34:35] op_sel:[1,0,0] op_sel_hi:[1,1,1]
	v_pk_mul_f32 v[20:21], v[20:21], v[168:169]
	v_add_f32_dpp v28, v46, v34 row_half_mirror row_mask:0xf bank_mask:0xf
	v_add_f32_dpp v32, v47, v35 row_half_mirror row_mask:0xf bank_mask:0xf
	v_pk_mul_f32 v[22:23], v[22:23], v[170:171]
	v_add_f32_dpp v28, v28, v28 row_ror:8 row_mask:0xf bank_mask:0xf
	v_add_f32_dpp v32, v32, v32 row_ror:8 row_mask:0xf bank_mask:0xf
	v_pk_mul_f32 v[24:25], v[24:25], v[168:169]
	v_add_f32_dpp v28, v28, v28 quad_perm:[1,0,3,2] row_mask:0xf bank_mask:0xf
	v_add_f32_dpp v32, v32, v32 quad_perm:[1,0,3,2] row_mask:0xf bank_mask:0xf
	v_pk_mul_f32 v[26:27], v[26:27], v[170:171]
	v_add_f32_dpp v28, v28, v28 quad_perm:[2,3,0,1] row_mask:0xf bank_mask:0xf
	v_add_f32_dpp v32, v32, v32 quad_perm:[2,3,0,1] row_mask:0xf bank_mask:0xf
	v_pk_fma_f32 v[20:21], v[180:181], v[8:9], v[20:21] op_sel_hi:[1,0,1]
	v_mov_b32_dpp v30, v28 row_half_mirror row_mask:0xf bank_mask:0xf
	v_pk_fma_f32 v[22:23], v[182:183], v[8:9], v[22:23] op_sel_hi:[1,0,1]
	v_pk_fma_f32 v[24:25], v[180:181], v[10:11], v[24:25] op_sel_hi:[1,0,1]
	v_pk_fma_f32 v[26:27], v[182:183], v[10:11], v[26:27] op_sel_hi:[1,0,1]
	v_pk_fma_f32 v[20:21], v[88:89], v[28:29], v[20:21] op_sel_hi:[1,0,1] neg_lo:[0,1,0] neg_hi:[0,1,0]
	v_pk_fma_f32 v[22:23], v[90:91], v[28:29], v[22:23] op_sel_hi:[1,0,1] neg_lo:[0,1,0] neg_hi:[0,1,0]
	v_pk_fma_f32 v[24:25], v[88:89], v[30:31], v[24:25] op_sel_hi:[1,0,1] neg_lo:[0,1,0] neg_hi:[0,1,0]
	v_pk_fma_f32 v[26:27], v[90:91], v[30:31], v[26:27] op_sel_hi:[1,0,1] neg_lo:[0,1,0] neg_hi:[0,1,0]
	v_add_f32_e32 v39, v32, v9
	ds_write_b32 v102, v39 offset:2944
	ds_read_b128 v[144:147], v195 offset:6400
	ds_read_b128 v[156:159], v195 offset:14592
	ds_read_b128 v[168:171], v195 offset:30976
	ds_read_b128 v[180:183], v195 offset:22784
	ds_read_b128 v[88:91], v195 offset:39168
	ds_read_b64 v[8:9], v196 offset:12800
	ds_read_b64 v[10:11], v36 offset:12800
	s_waitcnt lgkmcnt(8)
	v_pk_mul_f32 v[46:47], v[24:25], v[140:141] op_sel_hi:[0,1]
	v_pk_mul_f32 v[34:35], v[20:21], v[140:141] op_sel_hi:[0,1]
	v_pk_fma_f32 v[46:47], v[24:25], v[142:143], v[46:47] op_sel:[1,0,0] op_sel_hi:[1,1,1]
	v_pk_fma_f32 v[34:35], v[20:21], v[142:143], v[34:35] op_sel:[1,0,0] op_sel_hi:[1,1,1]
	v_pk_fma_f32 v[46:47], v[26:27], v[152:153], v[46:47] op_sel_hi:[0,1,1]
	v_pk_fma_f32 v[34:35], v[22:23], v[152:153], v[34:35] op_sel_hi:[0,1,1]
	v_pk_fma_f32 v[46:47], v[26:27], v[154:155], v[46:47] op_sel:[1,0,0] op_sel_hi:[1,1,1]
	v_pk_fma_f32 v[34:35], v[22:23], v[154:155], v[34:35] op_sel:[1,0,0] op_sel_hi:[1,1,1]
	v_pk_mul_f32 v[20:21], v[20:21], v[164:165]
	v_add_f32_dpp v28, v46, v34 row_half_mirror row_mask:0xf bank_mask:0xf
	v_add_f32_dpp v32, v47, v35 row_half_mirror row_mask:0xf bank_mask:0xf
	v_pk_mul_f32 v[22:23], v[22:23], v[166:167]
	v_add_f32_dpp v28, v28, v28 row_ror:8 row_mask:0xf bank_mask:0xf
	v_add_f32_dpp v32, v32, v32 row_ror:8 row_mask:0xf bank_mask:0xf
	v_pk_mul_f32 v[24:25], v[24:25], v[164:165]
	v_add_f32_dpp v28, v28, v28 quad_perm:[1,0,3,2] row_mask:0xf bank_mask:0xf
	v_add_f32_dpp v32, v32, v32 quad_perm:[1,0,3,2] row_mask:0xf bank_mask:0xf
	v_pk_mul_f32 v[26:27], v[26:27], v[166:167]
	v_add_f32_dpp v28, v28, v28 quad_perm:[2,3,0,1] row_mask:0xf bank_mask:0xf
	v_add_f32_dpp v32, v32, v32 quad_perm:[2,3,0,1] row_mask:0xf bank_mask:0xf
	v_pk_fma_f32 v[20:21], v[176:177], v[4:5], v[20:21] op_sel_hi:[1,0,1]
	v_mov_b32_dpp v30, v28 row_half_mirror row_mask:0xf bank_mask:0xf
	v_pk_fma_f32 v[22:23], v[178:179], v[4:5], v[22:23] op_sel_hi:[1,0,1]
	v_pk_fma_f32 v[24:25], v[176:177], v[6:7], v[24:25] op_sel_hi:[1,0,1]
	v_pk_fma_f32 v[26:27], v[178:179], v[6:7], v[26:27] op_sel_hi:[1,0,1]
	v_pk_fma_f32 v[20:21], v[84:85], v[28:29], v[20:21] op_sel_hi:[1,0,1] neg_lo:[0,1,0] neg_hi:[0,1,0]
	v_pk_fma_f32 v[22:23], v[86:87], v[28:29], v[22:23] op_sel_hi:[1,0,1] neg_lo:[0,1,0] neg_hi:[0,1,0]
	v_pk_fma_f32 v[24:25], v[84:85], v[30:31], v[24:25] op_sel_hi:[1,0,1] neg_lo:[0,1,0] neg_hi:[0,1,0]
	v_pk_fma_f32 v[26:27], v[86:87], v[30:31], v[26:27] op_sel_hi:[1,0,1] neg_lo:[0,1,0] neg_hi:[0,1,0]
	v_add_f32_e32 v39, v32, v5
	ds_write_b32 v102, v39 offset:3072
	ds_read_b128 v[140:143], v195 offset:6656
	ds_read_b128 v[152:155], v195 offset:14848
	ds_read_b128 v[164:167], v195 offset:31232
	ds_read_b128 v[176:179], v195 offset:23040
	ds_read_b128 v[84:87], v195 offset:39424
	ds_read_b64 v[4:5], v196 offset:13312
	ds_read_b64 v[6:7], v36 offset:13312
	s_waitcnt lgkmcnt(8)
	v_pk_mul_f32 v[46:47], v[24:25], v[144:145] op_sel_hi:[0,1]
	v_pk_mul_f32 v[34:35], v[20:21], v[144:145] op_sel_hi:[0,1]
	v_pk_fma_f32 v[46:47], v[24:25], v[146:147], v[46:47] op_sel:[1,0,0] op_sel_hi:[1,1,1]
	v_pk_fma_f32 v[34:35], v[20:21], v[146:147], v[34:35] op_sel:[1,0,0] op_sel_hi:[1,1,1]
	v_pk_fma_f32 v[46:47], v[26:27], v[156:157], v[46:47] op_sel_hi:[0,1,1]
	v_pk_fma_f32 v[34:35], v[22:23], v[156:157], v[34:35] op_sel_hi:[0,1,1]
	v_pk_fma_f32 v[46:47], v[26:27], v[158:159], v[46:47] op_sel:[1,0,0] op_sel_hi:[1,1,1]
	v_pk_fma_f32 v[34:35], v[22:23], v[158:159], v[34:35] op_sel:[1,0,0] op_sel_hi:[1,1,1]
	v_pk_mul_f32 v[20:21], v[20:21], v[168:169]
	v_add_f32_dpp v28, v46, v34 row_half_mirror row_mask:0xf bank_mask:0xf
	v_add_f32_dpp v32, v47, v35 row_half_mirror row_mask:0xf bank_mask:0xf
	v_pk_mul_f32 v[22:23], v[22:23], v[170:171]
	v_add_f32_dpp v28, v28, v28 row_ror:8 row_mask:0xf bank_mask:0xf
	v_add_f32_dpp v32, v32, v32 row_ror:8 row_mask:0xf bank_mask:0xf
	v_pk_mul_f32 v[24:25], v[24:25], v[168:169]
	v_add_f32_dpp v28, v28, v28 quad_perm:[1,0,3,2] row_mask:0xf bank_mask:0xf
	v_add_f32_dpp v32, v32, v32 quad_perm:[1,0,3,2] row_mask:0xf bank_mask:0xf
	v_pk_mul_f32 v[26:27], v[26:27], v[170:171]
	v_add_f32_dpp v28, v28, v28 quad_perm:[2,3,0,1] row_mask:0xf bank_mask:0xf
	v_add_f32_dpp v32, v32, v32 quad_perm:[2,3,0,1] row_mask:0xf bank_mask:0xf
	v_pk_fma_f32 v[20:21], v[180:181], v[8:9], v[20:21] op_sel_hi:[1,0,1]
	v_mov_b32_dpp v30, v28 row_half_mirror row_mask:0xf bank_mask:0xf
	v_pk_fma_f32 v[22:23], v[182:183], v[8:9], v[22:23] op_sel_hi:[1,0,1]
	v_pk_fma_f32 v[24:25], v[180:181], v[10:11], v[24:25] op_sel_hi:[1,0,1]
	v_pk_fma_f32 v[26:27], v[182:183], v[10:11], v[26:27] op_sel_hi:[1,0,1]
	v_pk_fma_f32 v[20:21], v[88:89], v[28:29], v[20:21] op_sel_hi:[1,0,1] neg_lo:[0,1,0] neg_hi:[0,1,0]
	v_pk_fma_f32 v[22:23], v[90:91], v[28:29], v[22:23] op_sel_hi:[1,0,1] neg_lo:[0,1,0] neg_hi:[0,1,0]
	v_pk_fma_f32 v[24:25], v[88:89], v[30:31], v[24:25] op_sel_hi:[1,0,1] neg_lo:[0,1,0] neg_hi:[0,1,0]
	v_pk_fma_f32 v[26:27], v[90:91], v[30:31], v[26:27] op_sel_hi:[1,0,1] neg_lo:[0,1,0] neg_hi:[0,1,0]
	v_add_f32_e32 v39, v32, v9
	ds_write_b32 v102, v39 offset:3200
	ds_read_b128 v[144:147], v195 offset:6912
	ds_read_b128 v[156:159], v195 offset:15104
	ds_read_b128 v[168:171], v195 offset:31488
	ds_read_b128 v[180:183], v195 offset:23296
	ds_read_b128 v[88:91], v195 offset:39680
	ds_read_b64 v[8:9], v196 offset:13824
	ds_read_b64 v[10:11], v36 offset:13824
	s_waitcnt lgkmcnt(8)
	v_pk_mul_f32 v[46:47], v[24:25], v[140:141] op_sel_hi:[0,1]
	v_pk_mul_f32 v[34:35], v[20:21], v[140:141] op_sel_hi:[0,1]
	v_pk_fma_f32 v[46:47], v[24:25], v[142:143], v[46:47] op_sel:[1,0,0] op_sel_hi:[1,1,1]
	v_pk_fma_f32 v[34:35], v[20:21], v[142:143], v[34:35] op_sel:[1,0,0] op_sel_hi:[1,1,1]
	v_pk_fma_f32 v[46:47], v[26:27], v[152:153], v[46:47] op_sel_hi:[0,1,1]
	v_pk_fma_f32 v[34:35], v[22:23], v[152:153], v[34:35] op_sel_hi:[0,1,1]
	v_pk_fma_f32 v[46:47], v[26:27], v[154:155], v[46:47] op_sel:[1,0,0] op_sel_hi:[1,1,1]
	v_pk_fma_f32 v[34:35], v[22:23], v[154:155], v[34:35] op_sel:[1,0,0] op_sel_hi:[1,1,1]
	v_pk_mul_f32 v[20:21], v[20:21], v[164:165]
	v_add_f32_dpp v28, v46, v34 row_half_mirror row_mask:0xf bank_mask:0xf
	v_add_f32_dpp v32, v47, v35 row_half_mirror row_mask:0xf bank_mask:0xf
	v_pk_mul_f32 v[22:23], v[22:23], v[166:167]
	v_add_f32_dpp v28, v28, v28 row_ror:8 row_mask:0xf bank_mask:0xf
	v_add_f32_dpp v32, v32, v32 row_ror:8 row_mask:0xf bank_mask:0xf
	v_pk_mul_f32 v[24:25], v[24:25], v[164:165]
	v_add_f32_dpp v28, v28, v28 quad_perm:[1,0,3,2] row_mask:0xf bank_mask:0xf
	v_add_f32_dpp v32, v32, v32 quad_perm:[1,0,3,2] row_mask:0xf bank_mask:0xf
	v_pk_mul_f32 v[26:27], v[26:27], v[166:167]
	v_add_f32_dpp v28, v28, v28 quad_perm:[2,3,0,1] row_mask:0xf bank_mask:0xf
	v_add_f32_dpp v32, v32, v32 quad_perm:[2,3,0,1] row_mask:0xf bank_mask:0xf
	v_pk_fma_f32 v[20:21], v[176:177], v[4:5], v[20:21] op_sel_hi:[1,0,1]
	v_mov_b32_dpp v30, v28 row_half_mirror row_mask:0xf bank_mask:0xf
	v_pk_fma_f32 v[22:23], v[178:179], v[4:5], v[22:23] op_sel_hi:[1,0,1]
	v_pk_fma_f32 v[24:25], v[176:177], v[6:7], v[24:25] op_sel_hi:[1,0,1]
	v_pk_fma_f32 v[26:27], v[178:179], v[6:7], v[26:27] op_sel_hi:[1,0,1]
	v_pk_fma_f32 v[20:21], v[84:85], v[28:29], v[20:21] op_sel_hi:[1,0,1] neg_lo:[0,1,0] neg_hi:[0,1,0]
	v_pk_fma_f32 v[22:23], v[86:87], v[28:29], v[22:23] op_sel_hi:[1,0,1] neg_lo:[0,1,0] neg_hi:[0,1,0]
	v_pk_fma_f32 v[24:25], v[84:85], v[30:31], v[24:25] op_sel_hi:[1,0,1] neg_lo:[0,1,0] neg_hi:[0,1,0]
	v_pk_fma_f32 v[26:27], v[86:87], v[30:31], v[26:27] op_sel_hi:[1,0,1] neg_lo:[0,1,0] neg_hi:[0,1,0]
	v_add_f32_e32 v39, v32, v5
	ds_write_b32 v102, v39 offset:3328
	ds_read_b128 v[140:143], v195 offset:7168
	ds_read_b128 v[152:155], v195 offset:15360
	ds_read_b128 v[164:167], v195 offset:31744
	ds_read_b128 v[176:179], v195 offset:23552
	ds_read_b128 v[84:87], v195 offset:39936
	ds_read_b64 v[4:5], v196 offset:14336
	ds_read_b64 v[6:7], v36 offset:14336
	s_waitcnt lgkmcnt(8)
	v_pk_mul_f32 v[46:47], v[24:25], v[144:145] op_sel_hi:[0,1]
	v_pk_mul_f32 v[34:35], v[20:21], v[144:145] op_sel_hi:[0,1]
	v_pk_fma_f32 v[46:47], v[24:25], v[146:147], v[46:47] op_sel:[1,0,0] op_sel_hi:[1,1,1]
	v_pk_fma_f32 v[34:35], v[20:21], v[146:147], v[34:35] op_sel:[1,0,0] op_sel_hi:[1,1,1]
	v_pk_fma_f32 v[46:47], v[26:27], v[156:157], v[46:47] op_sel_hi:[0,1,1]
	v_pk_fma_f32 v[34:35], v[22:23], v[156:157], v[34:35] op_sel_hi:[0,1,1]
	v_pk_fma_f32 v[46:47], v[26:27], v[158:159], v[46:47] op_sel:[1,0,0] op_sel_hi:[1,1,1]
	v_pk_fma_f32 v[34:35], v[22:23], v[158:159], v[34:35] op_sel:[1,0,0] op_sel_hi:[1,1,1]
	v_pk_mul_f32 v[20:21], v[20:21], v[168:169]
	v_add_f32_dpp v28, v46, v34 row_half_mirror row_mask:0xf bank_mask:0xf
	v_add_f32_dpp v32, v47, v35 row_half_mirror row_mask:0xf bank_mask:0xf
	v_pk_mul_f32 v[22:23], v[22:23], v[170:171]
	v_add_f32_dpp v28, v28, v28 row_ror:8 row_mask:0xf bank_mask:0xf
	v_add_f32_dpp v32, v32, v32 row_ror:8 row_mask:0xf bank_mask:0xf
	v_pk_mul_f32 v[24:25], v[24:25], v[168:169]
	v_add_f32_dpp v28, v28, v28 quad_perm:[1,0,3,2] row_mask:0xf bank_mask:0xf
	v_add_f32_dpp v32, v32, v32 quad_perm:[1,0,3,2] row_mask:0xf bank_mask:0xf
	v_pk_mul_f32 v[26:27], v[26:27], v[170:171]
	v_add_f32_dpp v28, v28, v28 quad_perm:[2,3,0,1] row_mask:0xf bank_mask:0xf
	v_add_f32_dpp v32, v32, v32 quad_perm:[2,3,0,1] row_mask:0xf bank_mask:0xf
	v_pk_fma_f32 v[20:21], v[180:181], v[8:9], v[20:21] op_sel_hi:[1,0,1]
	v_mov_b32_dpp v30, v28 row_half_mirror row_mask:0xf bank_mask:0xf
	v_pk_fma_f32 v[22:23], v[182:183], v[8:9], v[22:23] op_sel_hi:[1,0,1]
	v_pk_fma_f32 v[24:25], v[180:181], v[10:11], v[24:25] op_sel_hi:[1,0,1]
	v_pk_fma_f32 v[26:27], v[182:183], v[10:11], v[26:27] op_sel_hi:[1,0,1]
	v_pk_fma_f32 v[20:21], v[88:89], v[28:29], v[20:21] op_sel_hi:[1,0,1] neg_lo:[0,1,0] neg_hi:[0,1,0]
	v_pk_fma_f32 v[22:23], v[90:91], v[28:29], v[22:23] op_sel_hi:[1,0,1] neg_lo:[0,1,0] neg_hi:[0,1,0]
	v_pk_fma_f32 v[24:25], v[88:89], v[30:31], v[24:25] op_sel_hi:[1,0,1] neg_lo:[0,1,0] neg_hi:[0,1,0]
	v_pk_fma_f32 v[26:27], v[90:91], v[30:31], v[26:27] op_sel_hi:[1,0,1] neg_lo:[0,1,0] neg_hi:[0,1,0]
	v_add_f32_e32 v39, v32, v9
	ds_write_b32 v102, v39 offset:3456
	ds_read_b128 v[144:147], v195 offset:7424
	ds_read_b128 v[156:159], v195 offset:15616
	ds_read_b128 v[168:171], v195 offset:32000
	ds_read_b128 v[180:183], v195 offset:23808
	ds_read_b128 v[88:91], v195 offset:40192
	ds_read_b64 v[8:9], v196 offset:14848
	ds_read_b64 v[10:11], v36 offset:14848
	s_waitcnt lgkmcnt(8)
	v_pk_mul_f32 v[46:47], v[24:25], v[140:141] op_sel_hi:[0,1]
	v_pk_mul_f32 v[34:35], v[20:21], v[140:141] op_sel_hi:[0,1]
	v_pk_fma_f32 v[46:47], v[24:25], v[142:143], v[46:47] op_sel:[1,0,0] op_sel_hi:[1,1,1]
	v_pk_fma_f32 v[34:35], v[20:21], v[142:143], v[34:35] op_sel:[1,0,0] op_sel_hi:[1,1,1]
	v_pk_fma_f32 v[46:47], v[26:27], v[152:153], v[46:47] op_sel_hi:[0,1,1]
	v_pk_fma_f32 v[34:35], v[22:23], v[152:153], v[34:35] op_sel_hi:[0,1,1]
	v_pk_fma_f32 v[46:47], v[26:27], v[154:155], v[46:47] op_sel:[1,0,0] op_sel_hi:[1,1,1]
	v_pk_fma_f32 v[34:35], v[22:23], v[154:155], v[34:35] op_sel:[1,0,0] op_sel_hi:[1,1,1]
	v_pk_mul_f32 v[20:21], v[20:21], v[164:165]
	v_add_f32_dpp v28, v46, v34 row_half_mirror row_mask:0xf bank_mask:0xf
	v_add_f32_dpp v32, v47, v35 row_half_mirror row_mask:0xf bank_mask:0xf
	v_pk_mul_f32 v[22:23], v[22:23], v[166:167]
	v_add_f32_dpp v28, v28, v28 row_ror:8 row_mask:0xf bank_mask:0xf
	v_add_f32_dpp v32, v32, v32 row_ror:8 row_mask:0xf bank_mask:0xf
	v_pk_mul_f32 v[24:25], v[24:25], v[164:165]
	v_add_f32_dpp v28, v28, v28 quad_perm:[1,0,3,2] row_mask:0xf bank_mask:0xf
	v_add_f32_dpp v32, v32, v32 quad_perm:[1,0,3,2] row_mask:0xf bank_mask:0xf
	v_pk_mul_f32 v[26:27], v[26:27], v[166:167]
	v_add_f32_dpp v28, v28, v28 quad_perm:[2,3,0,1] row_mask:0xf bank_mask:0xf
	v_add_f32_dpp v32, v32, v32 quad_perm:[2,3,0,1] row_mask:0xf bank_mask:0xf
	v_pk_fma_f32 v[20:21], v[176:177], v[4:5], v[20:21] op_sel_hi:[1,0,1]
	v_mov_b32_dpp v30, v28 row_half_mirror row_mask:0xf bank_mask:0xf
	v_pk_fma_f32 v[22:23], v[178:179], v[4:5], v[22:23] op_sel_hi:[1,0,1]
	v_pk_fma_f32 v[24:25], v[176:177], v[6:7], v[24:25] op_sel_hi:[1,0,1]
	v_pk_fma_f32 v[26:27], v[178:179], v[6:7], v[26:27] op_sel_hi:[1,0,1]
	v_pk_fma_f32 v[20:21], v[84:85], v[28:29], v[20:21] op_sel_hi:[1,0,1] neg_lo:[0,1,0] neg_hi:[0,1,0]
	v_pk_fma_f32 v[22:23], v[86:87], v[28:29], v[22:23] op_sel_hi:[1,0,1] neg_lo:[0,1,0] neg_hi:[0,1,0]
	v_pk_fma_f32 v[24:25], v[84:85], v[30:31], v[24:25] op_sel_hi:[1,0,1] neg_lo:[0,1,0] neg_hi:[0,1,0]
	v_pk_fma_f32 v[26:27], v[86:87], v[30:31], v[26:27] op_sel_hi:[1,0,1] neg_lo:[0,1,0] neg_hi:[0,1,0]
	v_add_f32_e32 v39, v32, v5
	ds_write_b32 v102, v39 offset:3584
	ds_read_b128 v[140:143], v195 offset:7680
	ds_read_b128 v[152:155], v195 offset:15872
	ds_read_b128 v[164:167], v195 offset:32256
	ds_read_b128 v[176:179], v195 offset:24064
	ds_read_b128 v[84:87], v195 offset:40448
	ds_read_b64 v[4:5], v196 offset:15360
	ds_read_b64 v[6:7], v36 offset:15360
	s_waitcnt lgkmcnt(8)
	v_pk_mul_f32 v[46:47], v[24:25], v[144:145] op_sel_hi:[0,1]
	v_pk_mul_f32 v[34:35], v[20:21], v[144:145] op_sel_hi:[0,1]
	v_pk_fma_f32 v[46:47], v[24:25], v[146:147], v[46:47] op_sel:[1,0,0] op_sel_hi:[1,1,1]
	v_pk_fma_f32 v[34:35], v[20:21], v[146:147], v[34:35] op_sel:[1,0,0] op_sel_hi:[1,1,1]
	v_pk_fma_f32 v[46:47], v[26:27], v[156:157], v[46:47] op_sel_hi:[0,1,1]
	v_pk_fma_f32 v[34:35], v[22:23], v[156:157], v[34:35] op_sel_hi:[0,1,1]
	v_pk_fma_f32 v[46:47], v[26:27], v[158:159], v[46:47] op_sel:[1,0,0] op_sel_hi:[1,1,1]
	v_pk_fma_f32 v[34:35], v[22:23], v[158:159], v[34:35] op_sel:[1,0,0] op_sel_hi:[1,1,1]
	v_pk_mul_f32 v[20:21], v[20:21], v[168:169]
	v_add_f32_dpp v28, v46, v34 row_half_mirror row_mask:0xf bank_mask:0xf
	v_add_f32_dpp v32, v47, v35 row_half_mirror row_mask:0xf bank_mask:0xf
	v_pk_mul_f32 v[22:23], v[22:23], v[170:171]
	v_add_f32_dpp v28, v28, v28 row_ror:8 row_mask:0xf bank_mask:0xf
	v_add_f32_dpp v32, v32, v32 row_ror:8 row_mask:0xf bank_mask:0xf
	v_pk_mul_f32 v[24:25], v[24:25], v[168:169]
	v_add_f32_dpp v28, v28, v28 quad_perm:[1,0,3,2] row_mask:0xf bank_mask:0xf
	v_add_f32_dpp v32, v32, v32 quad_perm:[1,0,3,2] row_mask:0xf bank_mask:0xf
	v_pk_mul_f32 v[26:27], v[26:27], v[170:171]
	v_add_f32_dpp v28, v28, v28 quad_perm:[2,3,0,1] row_mask:0xf bank_mask:0xf
	v_add_f32_dpp v32, v32, v32 quad_perm:[2,3,0,1] row_mask:0xf bank_mask:0xf
	v_pk_fma_f32 v[20:21], v[180:181], v[8:9], v[20:21] op_sel_hi:[1,0,1]
	v_mov_b32_dpp v30, v28 row_half_mirror row_mask:0xf bank_mask:0xf
	v_pk_fma_f32 v[22:23], v[182:183], v[8:9], v[22:23] op_sel_hi:[1,0,1]
	v_pk_fma_f32 v[24:25], v[180:181], v[10:11], v[24:25] op_sel_hi:[1,0,1]
	v_pk_fma_f32 v[26:27], v[182:183], v[10:11], v[26:27] op_sel_hi:[1,0,1]
	v_pk_fma_f32 v[20:21], v[88:89], v[28:29], v[20:21] op_sel_hi:[1,0,1] neg_lo:[0,1,0] neg_hi:[0,1,0]
	v_pk_fma_f32 v[22:23], v[90:91], v[28:29], v[22:23] op_sel_hi:[1,0,1] neg_lo:[0,1,0] neg_hi:[0,1,0]
	v_pk_fma_f32 v[24:25], v[88:89], v[30:31], v[24:25] op_sel_hi:[1,0,1] neg_lo:[0,1,0] neg_hi:[0,1,0]
	v_pk_fma_f32 v[26:27], v[90:91], v[30:31], v[26:27] op_sel_hi:[1,0,1] neg_lo:[0,1,0] neg_hi:[0,1,0]
	v_add_f32_e32 v39, v32, v9
	ds_write_b32 v102, v39 offset:3712
	ds_read_b128 v[144:147], v195 offset:7936
	ds_read_b128 v[156:159], v195 offset:16128
	ds_read_b128 v[168:171], v195 offset:32512
	ds_read_b128 v[180:183], v195 offset:24320
	ds_read_b128 v[88:91], v195 offset:40704
	ds_read_b64 v[8:9], v196 offset:15872
	ds_read_b64 v[10:11], v36 offset:15872
	s_waitcnt lgkmcnt(8)
	v_pk_mul_f32 v[46:47], v[24:25], v[140:141] op_sel_hi:[0,1]
	v_pk_mul_f32 v[34:35], v[20:21], v[140:141] op_sel_hi:[0,1]
	v_pk_fma_f32 v[46:47], v[24:25], v[142:143], v[46:47] op_sel:[1,0,0] op_sel_hi:[1,1,1]
	v_pk_fma_f32 v[34:35], v[20:21], v[142:143], v[34:35] op_sel:[1,0,0] op_sel_hi:[1,1,1]
	v_pk_fma_f32 v[46:47], v[26:27], v[152:153], v[46:47] op_sel_hi:[0,1,1]
	v_pk_fma_f32 v[34:35], v[22:23], v[152:153], v[34:35] op_sel_hi:[0,1,1]
	v_pk_fma_f32 v[46:47], v[26:27], v[154:155], v[46:47] op_sel:[1,0,0] op_sel_hi:[1,1,1]
	v_pk_fma_f32 v[34:35], v[22:23], v[154:155], v[34:35] op_sel:[1,0,0] op_sel_hi:[1,1,1]
	v_pk_mul_f32 v[20:21], v[20:21], v[164:165]
	v_add_f32_dpp v28, v46, v34 row_half_mirror row_mask:0xf bank_mask:0xf
	v_add_f32_dpp v32, v47, v35 row_half_mirror row_mask:0xf bank_mask:0xf
	v_pk_mul_f32 v[22:23], v[22:23], v[166:167]
	v_add_f32_dpp v28, v28, v28 row_ror:8 row_mask:0xf bank_mask:0xf
	v_add_f32_dpp v32, v32, v32 row_ror:8 row_mask:0xf bank_mask:0xf
	v_pk_mul_f32 v[24:25], v[24:25], v[164:165]
	v_add_f32_dpp v28, v28, v28 quad_perm:[1,0,3,2] row_mask:0xf bank_mask:0xf
	v_add_f32_dpp v32, v32, v32 quad_perm:[1,0,3,2] row_mask:0xf bank_mask:0xf
	v_pk_mul_f32 v[26:27], v[26:27], v[166:167]
	v_add_f32_dpp v28, v28, v28 quad_perm:[2,3,0,1] row_mask:0xf bank_mask:0xf
	v_add_f32_dpp v32, v32, v32 quad_perm:[2,3,0,1] row_mask:0xf bank_mask:0xf
	v_pk_fma_f32 v[20:21], v[176:177], v[4:5], v[20:21] op_sel_hi:[1,0,1]
	v_mov_b32_dpp v30, v28 row_half_mirror row_mask:0xf bank_mask:0xf
	v_pk_fma_f32 v[22:23], v[178:179], v[4:5], v[22:23] op_sel_hi:[1,0,1]
	v_pk_fma_f32 v[24:25], v[176:177], v[6:7], v[24:25] op_sel_hi:[1,0,1]
	v_pk_fma_f32 v[26:27], v[178:179], v[6:7], v[26:27] op_sel_hi:[1,0,1]
	v_pk_fma_f32 v[20:21], v[84:85], v[28:29], v[20:21] op_sel_hi:[1,0,1] neg_lo:[0,1,0] neg_hi:[0,1,0]
	v_pk_fma_f32 v[22:23], v[86:87], v[28:29], v[22:23] op_sel_hi:[1,0,1] neg_lo:[0,1,0] neg_hi:[0,1,0]
	v_pk_fma_f32 v[24:25], v[84:85], v[30:31], v[24:25] op_sel_hi:[1,0,1] neg_lo:[0,1,0] neg_hi:[0,1,0]
	v_pk_fma_f32 v[26:27], v[86:87], v[30:31], v[26:27] op_sel_hi:[1,0,1] neg_lo:[0,1,0] neg_hi:[0,1,0]
	v_add_f32_e32 v39, v32, v5
	ds_write_b32 v102, v39 offset:3840
	s_waitcnt lgkmcnt(1)
	v_pk_mul_f32 v[46:47], v[24:25], v[144:145] op_sel_hi:[0,1]
	v_pk_mul_f32 v[34:35], v[20:21], v[144:145] op_sel_hi:[0,1]
	v_pk_fma_f32 v[46:47], v[24:25], v[146:147], v[46:47] op_sel:[1,0,0] op_sel_hi:[1,1,1]
	v_pk_fma_f32 v[34:35], v[20:21], v[146:147], v[34:35] op_sel:[1,0,0] op_sel_hi:[1,1,1]
	v_pk_fma_f32 v[46:47], v[26:27], v[156:157], v[46:47] op_sel_hi:[0,1,1]
	v_pk_fma_f32 v[34:35], v[22:23], v[156:157], v[34:35] op_sel_hi:[0,1,1]
	v_pk_fma_f32 v[46:47], v[26:27], v[158:159], v[46:47] op_sel:[1,0,0] op_sel_hi:[1,1,1]
	v_pk_fma_f32 v[34:35], v[22:23], v[158:159], v[34:35] op_sel:[1,0,0] op_sel_hi:[1,1,1]
	v_pk_mul_f32 v[20:21], v[20:21], v[168:169]
	v_add_f32_dpp v28, v46, v34 row_half_mirror row_mask:0xf bank_mask:0xf
	v_add_f32_dpp v32, v47, v35 row_half_mirror row_mask:0xf bank_mask:0xf
	v_pk_mul_f32 v[22:23], v[22:23], v[170:171]
	v_add_f32_dpp v28, v28, v28 row_ror:8 row_mask:0xf bank_mask:0xf
	v_add_f32_dpp v32, v32, v32 row_ror:8 row_mask:0xf bank_mask:0xf
	v_pk_mul_f32 v[24:25], v[24:25], v[168:169]
	v_add_f32_dpp v28, v28, v28 quad_perm:[1,0,3,2] row_mask:0xf bank_mask:0xf
	v_add_f32_dpp v32, v32, v32 quad_perm:[1,0,3,2] row_mask:0xf bank_mask:0xf
	v_pk_mul_f32 v[26:27], v[26:27], v[170:171]
	v_add_f32_dpp v28, v28, v28 quad_perm:[2,3,0,1] row_mask:0xf bank_mask:0xf
	v_add_f32_dpp v32, v32, v32 quad_perm:[2,3,0,1] row_mask:0xf bank_mask:0xf
	v_pk_fma_f32 v[20:21], v[180:181], v[8:9], v[20:21] op_sel_hi:[1,0,1]
	v_mov_b32_dpp v30, v28 row_half_mirror row_mask:0xf bank_mask:0xf
	v_pk_fma_f32 v[22:23], v[182:183], v[8:9], v[22:23] op_sel_hi:[1,0,1]
	v_pk_fma_f32 v[24:25], v[180:181], v[10:11], v[24:25] op_sel_hi:[1,0,1]
	v_pk_fma_f32 v[26:27], v[182:183], v[10:11], v[26:27] op_sel_hi:[1,0,1]
	v_pk_fma_f32 v[20:21], v[88:89], v[28:29], v[20:21] op_sel_hi:[1,0,1] neg_lo:[0,1,0] neg_hi:[0,1,0]
	v_pk_fma_f32 v[22:23], v[90:91], v[28:29], v[22:23] op_sel_hi:[1,0,1] neg_lo:[0,1,0] neg_hi:[0,1,0]
	v_pk_fma_f32 v[24:25], v[88:89], v[30:31], v[24:25] op_sel_hi:[1,0,1] neg_lo:[0,1,0] neg_hi:[0,1,0]
	v_pk_fma_f32 v[26:27], v[90:91], v[30:31], v[26:27] op_sel_hi:[1,0,1] neg_lo:[0,1,0] neg_hi:[0,1,0]
	v_add_f32_e32 v39, v32, v9
	ds_write_b32 v102, v39 offset:3968
	s_waitcnt lgkmcnt(0)
	s_barrier
	s_add_i32 s8, s8, 1
	s_cmp_eq_u32 s8, 64
	s_cbranch_scc0 .Lrw_scan_loop
	s_setprio 0
	s_branch .LBB0_183
